# HGRN2 epilogue: inlined ocml log1pf(-k) chains replaced by short f32 log/rcp sequence (same f32 math), on top of RN prefetch+rebalance
# speedup vs baseline: 1.0154x; 1.0154x over previous
.LBB0_2308:
	s_lshl_b32 s57, s8, 8
	s_add_i32 s57, s57, s80
	v_or_b32_e32 v150, s57, v204
	s_cmp_lt_i32 s64, 8
	s_mov_b64 s[6:7], -1
	s_cbranch_scc0 .LBB0_2350
	v_lshl_or_b32 v152, s64, 7, v206
	v_ashrrev_i32_e32 v153, 31, v152
	v_lshl_add_u64 v[154:155], v[152:153], 2, s[22:23]
	global_load_dwordx4 v[128:131], v[154:155], off
	v_mul_f32_e32 v140, 0x3fb8aa3b, v116
	v_mul_f32_e32 v151, 0x3fb8aa3b, v117
	v_exp_f32_e32 v140, v140
	v_exp_f32_e32 v151, v151
	v_mov_b64_e32 v[164:165], s[38:39]
	s_cmpk_gt_i32 s8, 0x7f
	v_add_f32_e32 v140, 1.0, v140
	v_add_f32_e32 v151, 1.0, v151
	v_rcp_f32_e32 v156, v140
	v_rcp_f32_e32 v157, v151
	s_cselect_b64 s[6:7], -1, 0
	s_cmpk_lt_i32 s8, 0x80
	s_cselect_b64 s[68:69], -1, 0
	s_waitcnt vmcnt(0)
	v_pk_add_f32 v[128:129], v[128:129], 1.0 op_sel_hi:[1,0] neg_lo:[1,0] neg_hi:[1,0]
	s_nop 0
	v_pk_mul_f32 v[156:157], v[156:157], v[128:129]
	v_pk_add_f32 v[130:131], v[130:131], 1.0 op_sel_hi:[1,0] neg_lo:[1,0] neg_hi:[1,0]
	v_sub_f32_e32 v159, 1.0, v157
	v_add_f32_e32 v151, -1.0, v159
	v_log_f32_e32 v159, v159
	v_rcp_f32_e32 v151, v151
	s_nop 0
	v_mul_f32_e32 v151, v157, v151
	v_mul_f32_e32 v159, 0x3f317218, v159
	v_cmp_eq_f32_e64 s[8:9], 0, v159
	v_mul_f32_e64 v151, -v159, v151
	s_nop 0
	v_cndmask_b32_e64 v159, v151, -v157, s[8:9]
	v_mul_f32_e32 v151, 0x3fb8aa3b, v119
	s_nop 0
	v_mov_b32_dpp v161, v159 row_shr:1 row_mask:0xf bank_mask:0xf bound_ctrl:1
	v_sub_f32_e32 v158, 1.0, v156
	v_add_f32_e32 v140, -1.0, v158
	v_log_f32_e32 v158, v158
	v_rcp_f32_e32 v140, v140
	s_nop 0
	v_mul_f32_e32 v140, v156, v140
	v_mul_f32_e32 v158, 0x3f317218, v158
	v_cmp_eq_f32_e64 s[8:9], 0, v158
	v_mul_f32_e64 v140, -v158, v140
	s_nop 0
	v_cndmask_b32_e64 v158, v140, -v156, s[8:9]
	v_mul_f32_e32 v140, 0x3fb8aa3b, v118
	v_exp_f32_e32 v140, v140
	v_mov_b32_dpp v160, v158 row_shr:1 row_mask:0xf bank_mask:0xf bound_ctrl:1
	v_pk_add_f32 v[158:159], v[158:159], v[160:161]
	v_exp_f32_e32 v151, v151
	v_add_f32_e32 v140, 1.0, v140
	v_mov_b32_dpp v160, v158 row_shr:2 row_mask:0xf bank_mask:0xf bound_ctrl:1
	v_mov_b32_dpp v161, v159 row_shr:2 row_mask:0xf bank_mask:0xf bound_ctrl:1
	v_pk_add_f32 v[158:159], v[158:159], v[160:161]
	s_nop 1
	v_mov_b32_dpp v160, v158 row_shr:4 row_mask:0xf bank_mask:0xf bound_ctrl:1
	v_mov_b32_dpp v161, v159 row_shr:4 row_mask:0xf bank_mask:0xf bound_ctrl:1
	v_pk_add_f32 v[158:159], v[158:159], v[160:161]
	s_nop 1
	v_mov_b32_dpp v160, v158 row_shr:8 row_mask:0xf bank_mask:0xf bound_ctrl:1
	v_mov_b32_dpp v161, v159 row_shr:8 row_mask:0xf bank_mask:0xf bound_ctrl:1
	v_pk_add_f32 v[162:163], v[158:159], v[160:161]
	v_rcp_f32_e32 v160, v140
	v_add_f32_e32 v140, 1.0, v151
	v_rcp_f32_e32 v161, v140
	ds_bpermute_b32 v158, v207, v162
	ds_bpermute_b32 v159, v207, v163
	v_pk_mul_f32 v[160:161], v[160:161], v[130:131]
	s_nop 0
	v_sub_f32_e32 v167, 1.0, v161
	v_add_f32_e32 v151, -1.0, v167
	v_log_f32_e32 v167, v167
	v_rcp_f32_e32 v151, v151
	s_nop 0
	v_mul_f32_e32 v151, v161, v151
	v_mul_f32_e32 v167, 0x3f317218, v167
	v_cmp_eq_f32_e64 s[8:9], 0, v167
	v_mul_f32_e64 v151, -v167, v151
	s_nop 0
	v_cndmask_b32_e64 v167, v151, -v161, s[8:9]
	v_mul_f32_e32 v151, 0x3fb8aa3b, v101
	v_exp_f32_e32 v151, v151
	v_sub_f32_e32 v166, 1.0, v160
	v_add_f32_e32 v140, -1.0, v166
	v_log_f32_e32 v166, v166
	v_rcp_f32_e32 v140, v140
	s_nop 0
	v_mul_f32_e32 v140, v160, v140
	v_mul_f32_e32 v166, 0x3f317218, v166
	v_cmp_eq_f32_e64 s[8:9], 0, v166
	v_mul_f32_e64 v140, -v166, v140
	s_nop 0
	v_cndmask_b32_e64 v166, v140, -v160, s[8:9]
	v_mul_f32_e32 v140, 0x3fb8aa3b, v100
	v_exp_f32_e32 v140, v140
	v_mov_b32_dpp v168, v166 row_shr:1 row_mask:0xf bank_mask:0xf bound_ctrl:1
	v_mov_b32_dpp v169, v167 row_shr:1 row_mask:0xf bank_mask:0xf bound_ctrl:1
	v_pk_add_f32 v[166:167], v[166:167], v[168:169]
	v_add_f32_e32 v140, 1.0, v140
	v_rcp_f32_e32 v172, v140
	v_mov_b32_dpp v168, v166 row_shr:2 row_mask:0xf bank_mask:0xf bound_ctrl:1
	v_mov_b32_dpp v169, v167 row_shr:2 row_mask:0xf bank_mask:0xf bound_ctrl:1
	v_add_f32_e32 v140, 1.0, v151
	v_pk_add_f32 v[166:167], v[166:167], v[168:169]
	v_rcp_f32_e32 v173, v140
	s_nop 0
	v_mov_b32_dpp v168, v166 row_shr:4 row_mask:0xf bank_mask:0xf bound_ctrl:1
	v_mov_b32_dpp v169, v167 row_shr:4 row_mask:0xf bank_mask:0xf bound_ctrl:1
	v_pk_add_f32 v[166:167], v[166:167], v[168:169]
	s_nop 1
	v_mov_b32_dpp v168, v166 row_shr:8 row_mask:0xf bank_mask:0xf bound_ctrl:1
	v_mov_b32_dpp v169, v167 row_shr:8 row_mask:0xf bank_mask:0xf bound_ctrl:1
	v_pk_add_f32 v[170:171], v[166:167], v[168:169]
	v_pk_mul_f32 v[166:167], v[172:173], v[128:129]
	ds_bpermute_b32 v168, v207, v170
	ds_bpermute_b32 v169, v207, v171
	v_sub_f32_e32 v173, 1.0, v167
	v_add_f32_e32 v151, -1.0, v173
	v_log_f32_e32 v173, v173
	v_rcp_f32_e32 v151, v151
	s_nop 0
	v_mul_f32_e32 v151, v167, v151
	v_mul_f32_e32 v173, 0x3f317218, v173
	v_cmp_eq_f32_e64 s[8:9], 0, v173
	v_mul_f32_e64 v151, -v173, v151
	s_nop 0
	v_cndmask_b32_e64 v173, v151, -v167, s[8:9]
	v_mul_f32_e32 v151, 0x3fb8aa3b, v103
	v_exp_f32_e32 v151, v151
	v_sub_f32_e32 v172, 1.0, v166
	v_add_f32_e32 v140, -1.0, v172
	v_log_f32_e32 v172, v172
	v_rcp_f32_e32 v140, v140
	s_nop 0
	v_mul_f32_e32 v140, v166, v140
	v_mul_f32_e32 v172, 0x3f317218, v172
	v_cmp_eq_f32_e64 s[8:9], 0, v172
	v_mul_f32_e64 v140, -v172, v140
	s_nop 0
	v_cndmask_b32_e64 v172, v140, -v166, s[8:9]
	v_mul_f32_e32 v140, 0x3fb8aa3b, v102
	v_exp_f32_e32 v140, v140
	v_mov_b32_dpp v174, v172 row_shr:1 row_mask:0xf bank_mask:0xf bound_ctrl:1
	v_mov_b32_dpp v175, v173 row_shr:1 row_mask:0xf bank_mask:0xf bound_ctrl:1
	v_pk_add_f32 v[172:173], v[172:173], v[174:175]
	v_add_f32_e32 v140, 1.0, v140
	v_rcp_f32_e32 v178, v140
	v_mov_b32_dpp v174, v172 row_shr:2 row_mask:0xf bank_mask:0xf bound_ctrl:1
	v_mov_b32_dpp v175, v173 row_shr:2 row_mask:0xf bank_mask:0xf bound_ctrl:1
	v_add_f32_e32 v140, 1.0, v151
	v_pk_add_f32 v[172:173], v[172:173], v[174:175]
	v_rcp_f32_e32 v179, v140
	s_nop 0
	v_mov_b32_dpp v174, v172 row_shr:4 row_mask:0xf bank_mask:0xf bound_ctrl:1
	v_mov_b32_dpp v175, v173 row_shr:4 row_mask:0xf bank_mask:0xf bound_ctrl:1
	v_pk_add_f32 v[172:173], v[172:173], v[174:175]
	s_nop 1
	v_mov_b32_dpp v174, v172 row_shr:8 row_mask:0xf bank_mask:0xf bound_ctrl:1
	v_mov_b32_dpp v175, v173 row_shr:8 row_mask:0xf bank_mask:0xf bound_ctrl:1
	v_pk_add_f32 v[176:177], v[172:173], v[174:175]
	v_pk_mul_f32 v[174:175], v[178:179], v[130:131]
	ds_bpermute_b32 v172, v207, v176
	ds_bpermute_b32 v173, v207, v177
	v_sub_f32_e32 v179, 1.0, v175
	v_add_f32_e32 v151, -1.0, v179
	v_log_f32_e32 v179, v179
	v_rcp_f32_e32 v151, v151
	s_nop 0
	v_mul_f32_e32 v151, v175, v151
	v_mul_f32_e32 v179, 0x3f317218, v179
	v_cmp_eq_f32_e64 s[8:9], 0, v179
	v_mul_f32_e64 v151, -v179, v151
	s_nop 0
	v_cndmask_b32_e64 v179, v151, -v175, s[8:9]
	v_mul_f32_e32 v151, 0x3fb8aa3b, v85
	v_exp_f32_e32 v151, v151
	v_sub_f32_e32 v178, 1.0, v174
	v_add_f32_e32 v140, -1.0, v178
	v_log_f32_e32 v178, v178
	v_rcp_f32_e32 v140, v140
	s_nop 0
	v_mul_f32_e32 v140, v174, v140
	v_mul_f32_e32 v178, 0x3f317218, v178
	v_cmp_eq_f32_e64 s[8:9], 0, v178
	v_mul_f32_e64 v140, -v178, v140
	s_nop 0
	v_cndmask_b32_e64 v178, v140, -v174, s[8:9]
	v_mul_f32_e32 v140, 0x3fb8aa3b, v84
	v_exp_f32_e32 v140, v140
	v_mov_b32_dpp v180, v178 row_shr:1 row_mask:0xf bank_mask:0xf bound_ctrl:1
	v_mov_b32_dpp v181, v179 row_shr:1 row_mask:0xf bank_mask:0xf bound_ctrl:1
	v_pk_add_f32 v[178:179], v[178:179], v[180:181]
	v_add_f32_e32 v140, 1.0, v140
	v_rcp_f32_e32 v184, v140
	v_mov_b32_dpp v180, v178 row_shr:2 row_mask:0xf bank_mask:0xf bound_ctrl:1
	v_mov_b32_dpp v181, v179 row_shr:2 row_mask:0xf bank_mask:0xf bound_ctrl:1
	v_add_f32_e32 v140, 1.0, v151
	v_pk_add_f32 v[178:179], v[178:179], v[180:181]
	v_rcp_f32_e32 v185, v140
	s_nop 0
	v_mov_b32_dpp v180, v178 row_shr:4 row_mask:0xf bank_mask:0xf bound_ctrl:1
	v_mov_b32_dpp v181, v179 row_shr:4 row_mask:0xf bank_mask:0xf bound_ctrl:1
	v_pk_add_f32 v[178:179], v[178:179], v[180:181]
	s_nop 1
	v_mov_b32_dpp v180, v178 row_shr:8 row_mask:0xf bank_mask:0xf bound_ctrl:1
	v_mov_b32_dpp v181, v179 row_shr:8 row_mask:0xf bank_mask:0xf bound_ctrl:1
	v_pk_add_f32 v[182:183], v[178:179], v[180:181]
	v_pk_mul_f32 v[178:179], v[184:185], v[128:129]
	ds_bpermute_b32 v180, v207, v182
	ds_bpermute_b32 v181, v207, v183
	v_sub_f32_e32 v185, 1.0, v179
	v_add_f32_e32 v151, -1.0, v185
	v_log_f32_e32 v185, v185
	v_rcp_f32_e32 v151, v151
	s_nop 0
	v_mul_f32_e32 v151, v179, v151
	v_mul_f32_e32 v185, 0x3f317218, v185
	v_cmp_eq_f32_e64 s[8:9], 0, v185
	v_mul_f32_e64 v151, -v185, v151
	s_nop 0
	v_cndmask_b32_e64 v185, v151, -v179, s[8:9]
	v_mul_f32_e32 v151, 0x3fb8aa3b, v87
	v_exp_f32_e32 v151, v151
	v_sub_f32_e32 v184, 1.0, v178
	v_add_f32_e32 v140, -1.0, v184
	v_log_f32_e32 v184, v184
	v_rcp_f32_e32 v140, v140
	s_nop 0
	v_mul_f32_e32 v140, v178, v140
	v_mul_f32_e32 v184, 0x3f317218, v184
	v_cmp_eq_f32_e64 s[8:9], 0, v184
	v_mul_f32_e64 v140, -v184, v140
	s_nop 0
	v_cndmask_b32_e64 v184, v140, -v178, s[8:9]
	v_mul_f32_e32 v140, 0x3fb8aa3b, v86
	v_exp_f32_e32 v140, v140
	v_mov_b32_dpp v186, v184 row_shr:1 row_mask:0xf bank_mask:0xf bound_ctrl:1
	v_mov_b32_dpp v187, v185 row_shr:1 row_mask:0xf bank_mask:0xf bound_ctrl:1
	v_pk_add_f32 v[184:185], v[184:185], v[186:187]
	v_add_f32_e32 v140, 1.0, v140
	v_rcp_f32_e32 v190, v140
	v_mov_b32_dpp v186, v184 row_shr:2 row_mask:0xf bank_mask:0xf bound_ctrl:1
	v_mov_b32_dpp v187, v185 row_shr:2 row_mask:0xf bank_mask:0xf bound_ctrl:1
	v_add_f32_e32 v140, 1.0, v151
	v_pk_add_f32 v[184:185], v[184:185], v[186:187]
	v_rcp_f32_e32 v191, v140
	s_nop 0
	v_mov_b32_dpp v186, v184 row_shr:4 row_mask:0xf bank_mask:0xf bound_ctrl:1
	v_mov_b32_dpp v187, v185 row_shr:4 row_mask:0xf bank_mask:0xf bound_ctrl:1
	v_pk_add_f32 v[184:185], v[184:185], v[186:187]
	s_nop 1
	v_mov_b32_dpp v186, v184 row_shr:8 row_mask:0xf bank_mask:0xf bound_ctrl:1
	v_mov_b32_dpp v187, v185 row_shr:8 row_mask:0xf bank_mask:0xf bound_ctrl:1
	v_pk_add_f32 v[188:189], v[184:185], v[186:187]
	v_pk_mul_f32 v[186:187], v[190:191], v[130:131]
	ds_bpermute_b32 v184, v207, v188
	ds_bpermute_b32 v185, v207, v189
	v_sub_f32_e32 v191, 1.0, v187
	v_add_f32_e32 v151, -1.0, v191
	v_log_f32_e32 v191, v191
	v_rcp_f32_e32 v151, v151
	s_nop 0
	v_mul_f32_e32 v151, v187, v151
	v_mul_f32_e32 v191, 0x3f317218, v191
	v_cmp_eq_f32_e64 s[8:9], 0, v191
	v_mul_f32_e64 v151, -v191, v151
	s_nop 0
	v_cndmask_b32_e64 v191, v151, -v187, s[8:9]
	v_mul_f32_e32 v151, 0x3fb8aa3b, v69
	v_exp_f32_e32 v151, v151
	v_sub_f32_e32 v190, 1.0, v186
	v_add_f32_e32 v140, -1.0, v190
	v_log_f32_e32 v190, v190
	v_rcp_f32_e32 v140, v140
	s_nop 0
	v_mul_f32_e32 v140, v186, v140
	v_mul_f32_e32 v190, 0x3f317218, v190
	v_cmp_eq_f32_e64 s[8:9], 0, v190
	v_mul_f32_e64 v140, -v190, v140
	s_nop 0
	v_cndmask_b32_e64 v190, v140, -v186, s[8:9]
	v_mul_f32_e32 v140, 0x3fb8aa3b, v68
	v_exp_f32_e32 v140, v140
	v_mov_b32_dpp v192, v190 row_shr:1 row_mask:0xf bank_mask:0xf bound_ctrl:1
	v_mov_b32_dpp v193, v191 row_shr:1 row_mask:0xf bank_mask:0xf bound_ctrl:1
	v_pk_add_f32 v[190:191], v[190:191], v[192:193]
	v_add_f32_e32 v140, 1.0, v140
	v_rcp_f32_e32 v196, v140
	v_mov_b32_dpp v192, v190 row_shr:2 row_mask:0xf bank_mask:0xf bound_ctrl:1
	v_mov_b32_dpp v193, v191 row_shr:2 row_mask:0xf bank_mask:0xf bound_ctrl:1
	v_add_f32_e32 v140, 1.0, v151
	v_pk_add_f32 v[190:191], v[190:191], v[192:193]
	v_rcp_f32_e32 v197, v140
	s_nop 0
	v_mov_b32_dpp v192, v190 row_shr:4 row_mask:0xf bank_mask:0xf bound_ctrl:1
	v_mov_b32_dpp v193, v191 row_shr:4 row_mask:0xf bank_mask:0xf bound_ctrl:1
	v_pk_add_f32 v[190:191], v[190:191], v[192:193]
	s_nop 1
	v_mov_b32_dpp v192, v190 row_shr:8 row_mask:0xf bank_mask:0xf bound_ctrl:1
	v_mov_b32_dpp v193, v191 row_shr:8 row_mask:0xf bank_mask:0xf bound_ctrl:1
	v_pk_add_f32 v[194:195], v[190:191], v[192:193]
	v_pk_mul_f32 v[190:191], v[196:197], v[128:129]
	ds_bpermute_b32 v192, v207, v194
	ds_bpermute_b32 v193, v207, v195
	v_sub_f32_e32 v197, 1.0, v191
	v_add_f32_e32 v151, -1.0, v197
	v_log_f32_e32 v197, v197
	v_rcp_f32_e32 v151, v151
	s_nop 0
	v_mul_f32_e32 v151, v191, v151
	v_mul_f32_e32 v197, 0x3f317218, v197
	v_cmp_eq_f32_e64 s[8:9], 0, v197
	v_mul_f32_e64 v151, -v197, v151
	s_nop 0
	v_cndmask_b32_e64 v197, v151, -v191, s[8:9]
	v_mul_f32_e32 v151, 0x3fb8aa3b, v71
	v_exp_f32_e32 v151, v151
	v_sub_f32_e32 v196, 1.0, v190
	v_add_f32_e32 v140, -1.0, v196
	v_log_f32_e32 v196, v196
	v_rcp_f32_e32 v140, v140
	s_nop 0
	v_mul_f32_e32 v140, v190, v140
	v_mul_f32_e32 v196, 0x3f317218, v196
	v_cmp_eq_f32_e64 s[8:9], 0, v196
	v_mul_f32_e64 v140, -v196, v140
	s_nop 0
	v_cndmask_b32_e64 v196, v140, -v190, s[8:9]
	v_mul_f32_e32 v140, 0x3fb8aa3b, v70
	v_exp_f32_e32 v140, v140
	v_mov_b32_dpp v198, v196 row_shr:1 row_mask:0xf bank_mask:0xf bound_ctrl:1
	v_mov_b32_dpp v199, v197 row_shr:1 row_mask:0xf bank_mask:0xf bound_ctrl:1
	v_pk_add_f32 v[196:197], v[196:197], v[198:199]
	v_add_f32_e32 v140, 1.0, v140
	v_rcp_f32_e32 v202, v140
	v_mov_b32_dpp v198, v196 row_shr:2 row_mask:0xf bank_mask:0xf bound_ctrl:1
	v_mov_b32_dpp v199, v197 row_shr:2 row_mask:0xf bank_mask:0xf bound_ctrl:1
	v_add_f32_e32 v140, 1.0, v151
	v_pk_add_f32 v[196:197], v[196:197], v[198:199]
	v_rcp_f32_e32 v203, v140
	s_nop 0
	v_mov_b32_dpp v198, v196 row_shr:4 row_mask:0xf bank_mask:0xf bound_ctrl:1
	v_mov_b32_dpp v199, v197 row_shr:4 row_mask:0xf bank_mask:0xf bound_ctrl:1
	v_pk_add_f32 v[196:197], v[196:197], v[198:199]
	s_nop 1
	v_mov_b32_dpp v198, v196 row_shr:8 row_mask:0xf bank_mask:0xf bound_ctrl:1
	v_mov_b32_dpp v199, v197 row_shr:8 row_mask:0xf bank_mask:0xf bound_ctrl:1
	v_pk_add_f32 v[200:201], v[196:197], v[198:199]
	v_pk_mul_f32 v[196:197], v[202:203], v[130:131]
	ds_bpermute_b32 v198, v207, v200
	ds_bpermute_b32 v199, v207, v201
	v_sub_f32_e32 v165, 1.0, v197
	v_add_f32_e32 v151, -1.0, v165
	v_log_f32_e32 v165, v165
	v_rcp_f32_e32 v151, v151
	s_nop 0
	v_mul_f32_e32 v151, v197, v151
	v_mul_f32_e32 v165, 0x3f317218, v165
	v_cmp_eq_f32_e64 s[8:9], 0, v165
	v_mul_f32_e64 v151, -v165, v151
	s_nop 0
	v_cndmask_b32_e64 v165, v151, -v197, s[8:9]
	s_and_b64 vcc, exec, s[6:7]
	s_nop 0
	v_mov_b32_dpp v203, v165 row_shr:1 row_mask:0xf bank_mask:0xf bound_ctrl:1
	v_sub_f32_e32 v164, 1.0, v196
	v_add_f32_e32 v140, -1.0, v164
	v_log_f32_e32 v164, v164
	v_rcp_f32_e32 v140, v140
	s_nop 0
	v_mul_f32_e32 v140, v196, v140
	v_mul_f32_e32 v164, 0x3f317218, v164
	v_cmp_eq_f32_e64 s[8:9], 0, v164
	v_mul_f32_e64 v140, -v164, v140
	s_nop 0
	v_cndmask_b32_e64 v164, v140, -v196, s[8:9]
	s_nop 1
	v_mov_b32_dpp v202, v164 row_shr:1 row_mask:0xf bank_mask:0xf bound_ctrl:1
	v_pk_add_f32 v[164:165], v[164:165], v[202:203]
	s_nop 1
	v_mov_b32_dpp v202, v164 row_shr:2 row_mask:0xf bank_mask:0xf bound_ctrl:1
	v_mov_b32_dpp v203, v165 row_shr:2 row_mask:0xf bank_mask:0xf bound_ctrl:1
	v_pk_add_f32 v[164:165], v[164:165], v[202:203]
	s_nop 1
	v_mov_b32_dpp v202, v164 row_shr:4 row_mask:0xf bank_mask:0xf bound_ctrl:1
	v_mov_b32_dpp v203, v165 row_shr:4 row_mask:0xf bank_mask:0xf bound_ctrl:1
	v_pk_add_f32 v[164:165], v[164:165], v[202:203]
	s_nop 1
	v_mov_b32_dpp v202, v164 row_shr:8 row_mask:0xf bank_mask:0xf bound_ctrl:1
	v_mov_b32_dpp v203, v165 row_shr:8 row_mask:0xf bank_mask:0xf bound_ctrl:1
	v_pk_add_f32 v[202:203], v[164:165], v[202:203]
	ds_bpermute_b32 v164, v207, v202
	ds_bpermute_b32 v165, v207, v203
	s_cbranch_vccnz .LBB0_2311
	s_waitcnt lgkmcnt(14)
	v_pk_add_f32 v[158:159], v[158:159], 0 op_sel_hi:[1,0]
	v_pk_add_f32 v[162:163], v[162:163], 0 op_sel_hi:[1,0]
	v_pk_add_f32 v[176:177], v[158:159], v[176:177]
	s_waitcnt lgkmcnt(10)
	v_pk_add_f32 v[158:159], v[158:159], v[172:173]
	v_pk_add_f32 v[170:171], v[170:171], 0 op_sel_hi:[1,0]
	s_waitcnt lgkmcnt(6)
	v_pk_add_f32 v[172:173], v[158:159], v[184:185]
	v_pk_add_f32 v[188:189], v[158:159], v[188:189]
	v_pk_add_f32 v[158:159], v[168:169], 0 op_sel_hi:[1,0]
	s_waitcnt lgkmcnt(2)
	v_pk_add_f32 v[184:185], v[172:173], v[198:199]
	v_pk_add_f32 v[182:183], v[158:159], v[182:183]
	v_pk_add_f32 v[158:159], v[158:159], v[180:181]
	v_pk_add_f32 v[200:201], v[172:173], v[200:201]
	v_pk_add_f32 v[168:169], v[158:159], v[192:193]
	v_pk_add_f32 v[194:195], v[158:159], v[194:195]
	s_waitcnt lgkmcnt(0)
	v_pk_add_f32 v[192:193], v[168:169], v[164:165]
	v_pk_add_f32 v[202:203], v[168:169], v[202:203]
	v_mov_b32_e32 v181, v193
	v_mov_b32_e32 v180, v192
	v_mov_b32_e32 v173, v185
	v_mov_b32_e32 v172, v184
	v_mov_b32_e32 v169, v193
	v_mov_b32_e32 v168, v192
	v_mov_b32_e32 v159, v185
	v_mov_b32_e32 v158, v184
	v_mov_b64_e32 v[164:165], v[192:193]
	v_mov_b64_e32 v[198:199], v[184:185]

.LBB0_2319:
	s_or_b64 exec, exec, s[8:9]
	v_mul_f32_e32 v140, 0x3fb8aa3b, v52
	v_mul_f32_e32 v151, 0x3fb8aa3b, v53
	v_exp_f32_e32 v140, v140
	v_exp_f32_e32 v151, v151
	v_add_f32_e32 v140, 1.0, v140
	v_add_f32_e32 v151, 1.0, v151
	v_rcp_f32_e32 v156, v140
	v_rcp_f32_e32 v157, v151
	s_nop 0
	v_pk_mul_f32 v[156:157], v[156:157], v[128:129]
	s_nop 0
	s_waitcnt lgkmcnt(1)
	s_waitcnt lgkmcnt(0)
	v_mov_b64_e32 v[166:167], s[38:39]
	v_sub_f32_e32 v159, 1.0, v157
	v_add_f32_e32 v151, -1.0, v159
	v_log_f32_e32 v159, v159
	v_rcp_f32_e32 v151, v151
	s_nop 0
	v_mul_f32_e32 v151, v157, v151
	v_mul_f32_e32 v159, 0x3f317218, v159
	v_cmp_eq_f32_e64 s[8:9], 0, v159
	v_mul_f32_e64 v151, -v159, v151
	s_nop 0
	v_cndmask_b32_e64 v159, v151, -v157, s[8:9]
	v_mul_f32_e32 v151, 0x3fb8aa3b, v55
	v_exp_f32_e32 v151, v151
	v_sub_f32_e32 v158, 1.0, v156
	v_add_f32_e32 v140, -1.0, v158
	v_log_f32_e32 v158, v158
	v_rcp_f32_e32 v140, v140
	s_nop 0
	v_mul_f32_e32 v140, v156, v140
	v_mul_f32_e32 v158, 0x3f317218, v158
	v_cmp_eq_f32_e64 s[8:9], 0, v158
	v_mul_f32_e64 v140, -v158, v140
	s_nop 0
	v_cndmask_b32_e64 v158, v140, -v156, s[8:9]
	v_mul_f32_e32 v140, 0x3fb8aa3b, v54
	v_exp_f32_e32 v140, v140
	v_mov_b32_dpp v160, v158 row_shr:1 row_mask:0xf bank_mask:0xf bound_ctrl:1
	v_mov_b32_dpp v161, v159 row_shr:1 row_mask:0xf bank_mask:0xf bound_ctrl:1
	v_pk_add_f32 v[158:159], v[158:159], v[160:161]
	v_add_f32_e32 v140, 1.0, v140
	v_rcp_f32_e32 v164, v140
	v_mov_b32_dpp v160, v158 row_shr:2 row_mask:0xf bank_mask:0xf bound_ctrl:1
	v_mov_b32_dpp v161, v159 row_shr:2 row_mask:0xf bank_mask:0xf bound_ctrl:1
	v_add_f32_e32 v140, 1.0, v151
	v_pk_add_f32 v[158:159], v[158:159], v[160:161]
	v_rcp_f32_e32 v165, v140
	s_nop 0
	v_mov_b32_dpp v160, v158 row_shr:4 row_mask:0xf bank_mask:0xf bound_ctrl:1
	v_mov_b32_dpp v161, v159 row_shr:4 row_mask:0xf bank_mask:0xf bound_ctrl:1
	v_pk_add_f32 v[158:159], v[158:159], v[160:161]
	s_nop 1
	v_mov_b32_dpp v160, v158 row_shr:8 row_mask:0xf bank_mask:0xf bound_ctrl:1
	v_mov_b32_dpp v161, v159 row_shr:8 row_mask:0xf bank_mask:0xf bound_ctrl:1
	v_pk_add_f32 v[162:163], v[158:159], v[160:161]
	v_pk_mul_f32 v[158:159], v[164:165], v[130:131]
	ds_bpermute_b32 v160, v207, v162
	ds_bpermute_b32 v161, v207, v163
	s_nop 0
	v_sub_f32_e32 v165, 1.0, v159
	v_add_f32_e32 v151, -1.0, v165
	v_log_f32_e32 v165, v165
	v_rcp_f32_e32 v151, v151
	s_nop 0
	v_mul_f32_e32 v151, v159, v151
	v_mul_f32_e32 v165, 0x3f317218, v165
	v_cmp_eq_f32_e64 s[8:9], 0, v165
	v_mul_f32_e64 v151, -v165, v151
	s_nop 0
	v_cndmask_b32_e64 v165, v151, -v159, s[8:9]
	v_mul_f32_e32 v151, 0x3fb8aa3b, v37
	v_exp_f32_e32 v151, v151
	v_sub_f32_e32 v164, 1.0, v158
	v_add_f32_e32 v140, -1.0, v164
	v_log_f32_e32 v164, v164
	v_rcp_f32_e32 v140, v140
	s_nop 0
	v_mul_f32_e32 v140, v158, v140
	v_mul_f32_e32 v164, 0x3f317218, v164
	v_cmp_eq_f32_e64 s[8:9], 0, v164
	v_mul_f32_e64 v140, -v164, v140
	s_nop 0
	v_cndmask_b32_e64 v164, v140, -v158, s[8:9]
	v_mul_f32_e32 v140, 0x3fb8aa3b, v36
	v_exp_f32_e32 v140, v140
	v_mov_b32_dpp v168, v164 row_shr:1 row_mask:0xf bank_mask:0xf bound_ctrl:1
	v_mov_b32_dpp v169, v165 row_shr:1 row_mask:0xf bank_mask:0xf bound_ctrl:1
	v_pk_add_f32 v[164:165], v[164:165], v[168:169]
	v_add_f32_e32 v140, 1.0, v140
	v_rcp_f32_e32 v172, v140
	v_mov_b32_dpp v168, v164 row_shr:2 row_mask:0xf bank_mask:0xf bound_ctrl:1
	v_mov_b32_dpp v169, v165 row_shr:2 row_mask:0xf bank_mask:0xf bound_ctrl:1
	v_add_f32_e32 v140, 1.0, v151
	v_pk_add_f32 v[164:165], v[164:165], v[168:169]
	v_rcp_f32_e32 v173, v140
	s_nop 0
	v_mov_b32_dpp v168, v164 row_shr:4 row_mask:0xf bank_mask:0xf bound_ctrl:1
	v_mov_b32_dpp v169, v165 row_shr:4 row_mask:0xf bank_mask:0xf bound_ctrl:1
	v_pk_add_f32 v[164:165], v[164:165], v[168:169]
	s_nop 1
	v_mov_b32_dpp v168, v164 row_shr:8 row_mask:0xf bank_mask:0xf bound_ctrl:1
	v_mov_b32_dpp v169, v165 row_shr:8 row_mask:0xf bank_mask:0xf bound_ctrl:1
	v_pk_add_f32 v[170:171], v[164:165], v[168:169]
	v_pk_mul_f32 v[164:165], v[172:173], v[128:129]
	ds_bpermute_b32 v168, v207, v170
	ds_bpermute_b32 v169, v207, v171
	v_sub_f32_e32 v173, 1.0, v165
	v_add_f32_e32 v151, -1.0, v173
	v_log_f32_e32 v173, v173
	v_rcp_f32_e32 v151, v151
	s_nop 0
	v_mul_f32_e32 v151, v165, v151
	v_mul_f32_e32 v173, 0x3f317218, v173
	v_cmp_eq_f32_e64 s[8:9], 0, v173
	v_mul_f32_e64 v151, -v173, v151
	s_nop 0
	v_cndmask_b32_e64 v173, v151, -v165, s[8:9]
	v_mul_f32_e32 v151, 0x3fb8aa3b, v39
	v_exp_f32_e32 v151, v151
	v_sub_f32_e32 v172, 1.0, v164
	v_add_f32_e32 v140, -1.0, v172
	v_log_f32_e32 v172, v172
	v_rcp_f32_e32 v140, v140
	s_nop 0
	v_mul_f32_e32 v140, v164, v140
	v_mul_f32_e32 v172, 0x3f317218, v172
	v_cmp_eq_f32_e64 s[8:9], 0, v172
	v_mul_f32_e64 v140, -v172, v140
	s_nop 0
	v_cndmask_b32_e64 v172, v140, -v164, s[8:9]
	v_mul_f32_e32 v140, 0x3fb8aa3b, v38
	v_exp_f32_e32 v140, v140
	v_mov_b32_dpp v174, v172 row_shr:1 row_mask:0xf bank_mask:0xf bound_ctrl:1
	v_mov_b32_dpp v175, v173 row_shr:1 row_mask:0xf bank_mask:0xf bound_ctrl:1
	v_pk_add_f32 v[172:173], v[172:173], v[174:175]
	v_add_f32_e32 v140, 1.0, v140
	v_rcp_f32_e32 v178, v140
	v_mov_b32_dpp v174, v172 row_shr:2 row_mask:0xf bank_mask:0xf bound_ctrl:1
	v_mov_b32_dpp v175, v173 row_shr:2 row_mask:0xf bank_mask:0xf bound_ctrl:1
	v_add_f32_e32 v140, 1.0, v151
	v_pk_add_f32 v[172:173], v[172:173], v[174:175]
	v_rcp_f32_e32 v179, v140
	s_nop 0
	v_mov_b32_dpp v174, v172 row_shr:4 row_mask:0xf bank_mask:0xf bound_ctrl:1
	v_mov_b32_dpp v175, v173 row_shr:4 row_mask:0xf bank_mask:0xf bound_ctrl:1
	v_pk_add_f32 v[172:173], v[172:173], v[174:175]
	s_nop 1
	v_mov_b32_dpp v174, v172 row_shr:8 row_mask:0xf bank_mask:0xf bound_ctrl:1
	v_mov_b32_dpp v175, v173 row_shr:8 row_mask:0xf bank_mask:0xf bound_ctrl:1
	v_pk_add_f32 v[176:177], v[172:173], v[174:175]
	v_pk_mul_f32 v[174:175], v[178:179], v[130:131]
	ds_bpermute_b32 v172, v207, v176
	ds_bpermute_b32 v173, v207, v177
	v_sub_f32_e32 v179, 1.0, v175
	v_add_f32_e32 v151, -1.0, v179
	v_log_f32_e32 v179, v179
	v_rcp_f32_e32 v151, v151
	s_nop 0
	v_mul_f32_e32 v151, v175, v151
	v_mul_f32_e32 v179, 0x3f317218, v179
	v_cmp_eq_f32_e64 s[8:9], 0, v179
	v_mul_f32_e64 v151, -v179, v151
	s_nop 0
	v_cndmask_b32_e64 v179, v151, -v175, s[8:9]
	v_mul_f32_e32 v151, 0x3fb8aa3b, v21
	v_exp_f32_e32 v151, v151
	v_sub_f32_e32 v178, 1.0, v174
	v_add_f32_e32 v140, -1.0, v178
	v_log_f32_e32 v178, v178
	v_rcp_f32_e32 v140, v140
	s_nop 0
	v_mul_f32_e32 v140, v174, v140
	v_mul_f32_e32 v178, 0x3f317218, v178
	v_cmp_eq_f32_e64 s[8:9], 0, v178
	v_mul_f32_e64 v140, -v178, v140
	s_nop 0
	v_cndmask_b32_e64 v178, v140, -v174, s[8:9]
	v_mul_f32_e32 v140, 0x3fb8aa3b, v20
	v_exp_f32_e32 v140, v140
	v_mov_b32_dpp v180, v178 row_shr:1 row_mask:0xf bank_mask:0xf bound_ctrl:1
	v_mov_b32_dpp v181, v179 row_shr:1 row_mask:0xf bank_mask:0xf bound_ctrl:1
	v_pk_add_f32 v[178:179], v[178:179], v[180:181]
	v_add_f32_e32 v140, 1.0, v140
	v_rcp_f32_e32 v184, v140
	v_mov_b32_dpp v180, v178 row_shr:2 row_mask:0xf bank_mask:0xf bound_ctrl:1
	v_mov_b32_dpp v181, v179 row_shr:2 row_mask:0xf bank_mask:0xf bound_ctrl:1
	v_add_f32_e32 v140, 1.0, v151
	v_pk_add_f32 v[178:179], v[178:179], v[180:181]
	v_rcp_f32_e32 v185, v140
	s_nop 0
	v_mov_b32_dpp v180, v178 row_shr:4 row_mask:0xf bank_mask:0xf bound_ctrl:1
	v_mov_b32_dpp v181, v179 row_shr:4 row_mask:0xf bank_mask:0xf bound_ctrl:1
	v_pk_add_f32 v[178:179], v[178:179], v[180:181]
	s_nop 1
	v_mov_b32_dpp v180, v178 row_shr:8 row_mask:0xf bank_mask:0xf bound_ctrl:1
	v_mov_b32_dpp v181, v179 row_shr:8 row_mask:0xf bank_mask:0xf bound_ctrl:1
	v_pk_add_f32 v[182:183], v[178:179], v[180:181]
	v_pk_mul_f32 v[178:179], v[184:185], v[128:129]
	ds_bpermute_b32 v180, v207, v182
	ds_bpermute_b32 v181, v207, v183
	v_sub_f32_e32 v185, 1.0, v179
	v_add_f32_e32 v151, -1.0, v185
	v_log_f32_e32 v185, v185
	v_rcp_f32_e32 v151, v151
	s_nop 0
	v_mul_f32_e32 v151, v179, v151
	v_mul_f32_e32 v185, 0x3f317218, v185
	v_cmp_eq_f32_e64 s[8:9], 0, v185
	v_mul_f32_e64 v151, -v185, v151
	s_nop 0
	v_cndmask_b32_e64 v185, v151, -v179, s[8:9]
	v_mul_f32_e32 v151, 0x3fb8aa3b, v23
	v_exp_f32_e32 v151, v151
	v_sub_f32_e32 v184, 1.0, v178
	v_add_f32_e32 v140, -1.0, v184
	v_log_f32_e32 v184, v184
	v_rcp_f32_e32 v140, v140
	s_nop 0
	v_mul_f32_e32 v140, v178, v140
	v_mul_f32_e32 v184, 0x3f317218, v184
	v_cmp_eq_f32_e64 s[8:9], 0, v184
	v_mul_f32_e64 v140, -v184, v140
	s_nop 0
	v_cndmask_b32_e64 v184, v140, -v178, s[8:9]
	v_mul_f32_e32 v140, 0x3fb8aa3b, v22
	v_exp_f32_e32 v140, v140
	v_mov_b32_dpp v186, v184 row_shr:1 row_mask:0xf bank_mask:0xf bound_ctrl:1
	v_mov_b32_dpp v187, v185 row_shr:1 row_mask:0xf bank_mask:0xf bound_ctrl:1
	v_pk_add_f32 v[184:185], v[184:185], v[186:187]
	v_add_f32_e32 v140, 1.0, v140
	v_rcp_f32_e32 v190, v140
	v_mov_b32_dpp v186, v184 row_shr:2 row_mask:0xf bank_mask:0xf bound_ctrl:1
	v_mov_b32_dpp v187, v185 row_shr:2 row_mask:0xf bank_mask:0xf bound_ctrl:1
	v_add_f32_e32 v140, 1.0, v151
	v_pk_add_f32 v[184:185], v[184:185], v[186:187]
	v_rcp_f32_e32 v191, v140
	s_nop 0
	v_mov_b32_dpp v186, v184 row_shr:4 row_mask:0xf bank_mask:0xf bound_ctrl:1
	v_mov_b32_dpp v187, v185 row_shr:4 row_mask:0xf bank_mask:0xf bound_ctrl:1
	v_pk_add_f32 v[184:185], v[184:185], v[186:187]
	s_nop 1
	v_mov_b32_dpp v186, v184 row_shr:8 row_mask:0xf bank_mask:0xf bound_ctrl:1
	v_mov_b32_dpp v187, v185 row_shr:8 row_mask:0xf bank_mask:0xf bound_ctrl:1
	v_pk_add_f32 v[188:189], v[184:185], v[186:187]
	v_pk_mul_f32 v[186:187], v[190:191], v[130:131]
	ds_bpermute_b32 v184, v207, v188
	ds_bpermute_b32 v185, v207, v189
	v_sub_f32_e32 v191, 1.0, v187
	v_add_f32_e32 v151, -1.0, v191
	v_log_f32_e32 v191, v191
	v_rcp_f32_e32 v151, v151
	s_nop 0
	v_mul_f32_e32 v151, v187, v151
	v_mul_f32_e32 v191, 0x3f317218, v191
	v_cmp_eq_f32_e64 s[8:9], 0, v191
	v_mul_f32_e64 v151, -v191, v151
	s_nop 0
	v_cndmask_b32_e64 v191, v151, -v187, s[8:9]
	v_mul_f32_e32 v151, 0x3fb8aa3b, v5
	v_exp_f32_e32 v151, v151
	v_sub_f32_e32 v190, 1.0, v186
	v_add_f32_e32 v140, -1.0, v190
	v_log_f32_e32 v190, v190
	v_rcp_f32_e32 v140, v140
	s_nop 0
	v_mul_f32_e32 v140, v186, v140
	v_mul_f32_e32 v190, 0x3f317218, v190
	v_cmp_eq_f32_e64 s[8:9], 0, v190
	v_mul_f32_e64 v140, -v190, v140
	s_nop 0
	v_cndmask_b32_e64 v190, v140, -v186, s[8:9]
	v_mul_f32_e32 v140, 0x3fb8aa3b, v4
	v_exp_f32_e32 v140, v140
	v_mov_b32_dpp v192, v190 row_shr:1 row_mask:0xf bank_mask:0xf bound_ctrl:1
	v_mov_b32_dpp v193, v191 row_shr:1 row_mask:0xf bank_mask:0xf bound_ctrl:1
	v_pk_add_f32 v[190:191], v[190:191], v[192:193]
	v_add_f32_e32 v140, 1.0, v140
	v_rcp_f32_e32 v194, v140
	v_add_f32_e32 v140, 1.0, v151
	v_rcp_f32_e32 v195, v140
	v_mov_b32_dpp v192, v190 row_shr:2 row_mask:0xf bank_mask:0xf bound_ctrl:1
	v_mov_b32_dpp v193, v191 row_shr:2 row_mask:0xf bank_mask:0xf bound_ctrl:1
	v_pk_add_f32 v[190:191], v[190:191], v[192:193]
	v_pk_mul_f32 v[128:129], v[194:195], v[128:129]
	s_nop 0
	v_mov_b32_dpp v192, v190 row_shr:4 row_mask:0xf bank_mask:0xf bound_ctrl:1
	v_mov_b32_dpp v193, v191 row_shr:4 row_mask:0xf bank_mask:0xf bound_ctrl:1
	v_pk_add_f32 v[190:191], v[190:191], v[192:193]
	s_nop 1
	v_mov_b32_dpp v192, v190 row_shr:8 row_mask:0xf bank_mask:0xf bound_ctrl:1
	v_mov_b32_dpp v193, v191 row_shr:8 row_mask:0xf bank_mask:0xf bound_ctrl:1
	v_pk_add_f32 v[192:193], v[190:191], v[192:193]
	ds_bpermute_b32 v190, v207, v192
	ds_bpermute_b32 v191, v207, v193
	v_sub_f32_e32 v195, 1.0, v129
	v_add_f32_e32 v151, -1.0, v195
	v_log_f32_e32 v195, v195
	v_rcp_f32_e32 v151, v151
	s_nop 0
	v_mul_f32_e32 v151, v129, v151
	v_mul_f32_e32 v195, 0x3f317218, v195
	v_cmp_eq_f32_e64 s[8:9], 0, v195
	v_mul_f32_e64 v151, -v195, v151
	s_nop 0
	v_cndmask_b32_e64 v195, v151, -v129, s[8:9]
	v_mul_f32_e32 v151, 0x3fb8aa3b, v7
	v_exp_f32_e32 v151, v151
	v_sub_f32_e32 v194, 1.0, v128
	v_add_f32_e32 v140, -1.0, v194
	v_log_f32_e32 v194, v194
	v_rcp_f32_e32 v140, v140
	s_nop 0
	v_mul_f32_e32 v140, v128, v140
	v_mul_f32_e32 v194, 0x3f317218, v194
	v_cmp_eq_f32_e64 s[8:9], 0, v194
	v_mul_f32_e64 v140, -v194, v140
	s_nop 0
	v_cndmask_b32_e64 v194, v140, -v128, s[8:9]
	v_mul_f32_e32 v140, 0x3fb8aa3b, v6
	v_exp_f32_e32 v140, v140
	v_mov_b32_dpp v196, v194 row_shr:1 row_mask:0xf bank_mask:0xf bound_ctrl:1
	v_mov_b32_dpp v197, v195 row_shr:1 row_mask:0xf bank_mask:0xf bound_ctrl:1
	v_pk_add_f32 v[194:195], v[194:195], v[196:197]
	v_add_f32_e32 v140, 1.0, v140
	v_rcp_f32_e32 v198, v140
	v_add_f32_e32 v140, 1.0, v151
	v_rcp_f32_e32 v199, v140
	v_mov_b32_dpp v196, v194 row_shr:2 row_mask:0xf bank_mask:0xf bound_ctrl:1
	v_mov_b32_dpp v197, v195 row_shr:2 row_mask:0xf bank_mask:0xf bound_ctrl:1
	v_pk_add_f32 v[194:195], v[194:195], v[196:197]
	v_pk_mul_f32 v[130:131], v[198:199], v[130:131]
	s_nop 0
	v_mov_b32_dpp v196, v194 row_shr:4 row_mask:0xf bank_mask:0xf bound_ctrl:1
	v_mov_b32_dpp v197, v195 row_shr:4 row_mask:0xf bank_mask:0xf bound_ctrl:1
	v_pk_add_f32 v[194:195], v[194:195], v[196:197]
	s_nop 1
	v_mov_b32_dpp v196, v194 row_shr:8 row_mask:0xf bank_mask:0xf bound_ctrl:1
	v_mov_b32_dpp v197, v195 row_shr:8 row_mask:0xf bank_mask:0xf bound_ctrl:1
	v_pk_add_f32 v[196:197], v[194:195], v[196:197]
	ds_bpermute_b32 v194, v207, v196
	ds_bpermute_b32 v195, v207, v197
	v_sub_f32_e32 v167, 1.0, v131
	v_add_f32_e32 v151, -1.0, v167
	v_log_f32_e32 v167, v167
	v_rcp_f32_e32 v151, v151
	s_nop 0
	v_mul_f32_e32 v151, v131, v151
	v_mul_f32_e32 v167, 0x3f317218, v167
	v_cmp_eq_f32_e64 s[8:9], 0, v167
	v_mul_f32_e64 v151, -v167, v151
	s_nop 0
	v_cndmask_b32_e64 v167, v151, -v131, s[8:9]
	s_andn2_b64 vcc, exec, s[68:69]
	s_nop 0
	v_mov_b32_dpp v199, v167 row_shr:1 row_mask:0xf bank_mask:0xf bound_ctrl:1
	v_sub_f32_e32 v166, 1.0, v130
	v_add_f32_e32 v140, -1.0, v166
	v_log_f32_e32 v166, v166
	v_rcp_f32_e32 v140, v140
	s_nop 0
	v_mul_f32_e32 v140, v130, v140
	v_mul_f32_e32 v166, 0x3f317218, v166
	v_cmp_eq_f32_e64 s[8:9], 0, v166
	v_mul_f32_e64 v140, -v166, v140
	s_nop 0
	v_cndmask_b32_e64 v166, v140, -v130, s[8:9]
	v_cndmask_b32_e64 v140, 0, 1, s[68:69]
	v_cmp_ne_u32_e64 s[8:9], 1, v140
	v_mov_b32_dpp v198, v166 row_shr:1 row_mask:0xf bank_mask:0xf bound_ctrl:1
	v_pk_add_f32 v[166:167], v[166:167], v[198:199]
	s_nop 1
	v_mov_b32_dpp v198, v166 row_shr:2 row_mask:0xf bank_mask:0xf bound_ctrl:1
	v_mov_b32_dpp v199, v167 row_shr:2 row_mask:0xf bank_mask:0xf bound_ctrl:1
	v_pk_add_f32 v[166:167], v[166:167], v[198:199]
	s_nop 1
	v_mov_b32_dpp v198, v166 row_shr:4 row_mask:0xf bank_mask:0xf bound_ctrl:1
	v_mov_b32_dpp v199, v167 row_shr:4 row_mask:0xf bank_mask:0xf bound_ctrl:1
	v_pk_add_f32 v[166:167], v[166:167], v[198:199]
	s_nop 1
	v_mov_b32_dpp v198, v166 row_shr:8 row_mask:0xf bank_mask:0xf bound_ctrl:1
	v_mov_b32_dpp v199, v167 row_shr:8 row_mask:0xf bank_mask:0xf bound_ctrl:1
	v_pk_add_f32 v[198:199], v[166:167], v[198:199]
	ds_bpermute_b32 v166, v207, v198
	ds_bpermute_b32 v167, v207, v199
	s_cbranch_vccnz .LBB0_2321
	s_waitcnt lgkmcnt(14)
	v_pk_add_f32 v[160:161], v[160:161], 0 op_sel_hi:[1,0]
	v_pk_add_f32 v[162:163], v[162:163], 0 op_sel_hi:[1,0]
	v_pk_add_f32 v[176:177], v[160:161], v[176:177]
	s_waitcnt lgkmcnt(10)
	v_pk_add_f32 v[160:161], v[160:161], v[172:173]
	v_pk_add_f32 v[170:171], v[170:171], 0 op_sel_hi:[1,0]
	s_waitcnt lgkmcnt(6)
	v_pk_add_f32 v[172:173], v[160:161], v[184:185]
	v_pk_add_f32 v[188:189], v[160:161], v[188:189]
	v_pk_add_f32 v[160:161], v[168:169], 0 op_sel_hi:[1,0]
	s_waitcnt lgkmcnt(2)
	v_pk_add_f32 v[184:185], v[172:173], v[194:195]
	v_pk_add_f32 v[182:183], v[160:161], v[182:183]
	v_pk_add_f32 v[160:161], v[160:161], v[180:181]
	v_pk_add_f32 v[196:197], v[172:173], v[196:197]
	v_pk_add_f32 v[168:169], v[160:161], v[190:191]
	v_pk_add_f32 v[192:193], v[160:161], v[192:193]
	s_waitcnt lgkmcnt(0)
	v_pk_add_f32 v[190:191], v[168:169], v[166:167]
	v_pk_add_f32 v[198:199], v[168:169], v[198:199]
	v_mov_b32_e32 v181, v191
	v_mov_b32_e32 v180, v190
	v_mov_b32_e32 v173, v185
	v_mov_b32_e32 v172, v184
	v_mov_b32_e32 v169, v191
	v_mov_b32_e32 v168, v190
	v_mov_b32_e32 v161, v185
	v_mov_b32_e32 v160, v184
	v_mov_b64_e32 v[166:167], v[190:191]
	v_mov_b64_e32 v[194:195], v[184:185]

.LBB0_2329:
	s_or_b64 exec, exec, s[68:69]
	global_load_dwordx4 v[128:131], v[154:155], off offset:16
	v_mul_f32_e32 v140, 0x3fb8aa3b, v112
	v_mul_f32_e32 v154, 0x3fb8aa3b, v113
	v_exp_f32_e32 v140, v140
	v_exp_f32_e32 v154, v154
	v_mov_b64_e32 v[162:163], s[38:39]
	v_add_f32_e32 v140, 1.0, v140
	v_add_f32_e32 v155, 1.0, v154
	v_rcp_f32_e32 v154, v140
	v_rcp_f32_e32 v155, v155
	s_waitcnt vmcnt(0)
	v_pk_add_f32 v[128:129], v[128:129], 1.0 op_sel_hi:[1,0] neg_lo:[1,0] neg_hi:[1,0]
	s_nop 0
	v_pk_mul_f32 v[154:155], v[154:155], v[128:129]
	v_pk_add_f32 v[130:131], v[130:131], 1.0 op_sel_hi:[1,0] neg_lo:[1,0] neg_hi:[1,0]
	s_waitcnt lgkmcnt(1)
	s_waitcnt lgkmcnt(0)
	v_mul_f32_e32 v160, 0x3fb8aa3b, v115
	v_exp_f32_e32 v164, v160
	v_sub_f32_e32 v157, 1.0, v155
	v_add_f32_e32 v156, -1.0, v157
	v_log_f32_e32 v157, v157
	v_rcp_f32_e32 v156, v156
	s_nop 0
	v_mul_f32_e32 v156, v155, v156
	v_mul_f32_e32 v157, 0x3f317218, v157
	v_cmp_eq_f32_e64 s[34:35], 0, v157
	v_mul_f32_e64 v156, -v157, v156
	s_nop 0
	v_cndmask_b32_e64 v157, v156, -v155, s[34:35]
	s_nop 0
	s_nop 0
	v_mov_b32_dpp v159, v157 row_shr:1 row_mask:0xf bank_mask:0xf bound_ctrl:1
	v_sub_f32_e32 v156, 1.0, v154
	v_add_f32_e32 v140, -1.0, v156
	v_log_f32_e32 v156, v156
	v_rcp_f32_e32 v140, v140
	s_nop 0
	v_mul_f32_e32 v140, v154, v140
	v_mul_f32_e32 v156, 0x3f317218, v156
	v_cmp_eq_f32_e64 s[34:35], 0, v156
	v_mul_f32_e64 v140, -v156, v140
	s_nop 0
	v_cndmask_b32_e64 v156, v140, -v154, s[34:35]
	v_mul_f32_e32 v140, 0x3fb8aa3b, v114
	v_exp_f32_e32 v140, v140
	v_mov_b32_dpp v158, v156 row_shr:1 row_mask:0xf bank_mask:0xf bound_ctrl:1
	v_pk_add_f32 v[156:157], v[156:157], v[158:159]
	v_add_f32_e32 v140, 1.0, v140
	s_nop 0
	v_mov_b32_dpp v158, v156 row_shr:2 row_mask:0xf bank_mask:0xf bound_ctrl:1
	v_mov_b32_dpp v159, v157 row_shr:2 row_mask:0xf bank_mask:0xf bound_ctrl:1
	v_pk_add_f32 v[156:157], v[156:157], v[158:159]
	s_nop 1
	v_mov_b32_dpp v158, v156 row_shr:4 row_mask:0xf bank_mask:0xf bound_ctrl:1
	v_mov_b32_dpp v159, v157 row_shr:4 row_mask:0xf bank_mask:0xf bound_ctrl:1
	v_pk_add_f32 v[156:157], v[156:157], v[158:159]
	s_nop 1
	v_mov_b32_dpp v158, v156 row_shr:8 row_mask:0xf bank_mask:0xf bound_ctrl:1
	v_mov_b32_dpp v159, v157 row_shr:8 row_mask:0xf bank_mask:0xf bound_ctrl:1
	v_pk_add_f32 v[160:161], v[156:157], v[158:159]
	v_rcp_f32_e32 v156, v140
	v_add_f32_e32 v140, 1.0, v164
	v_rcp_f32_e32 v157, v140
	ds_bpermute_b32 v158, v207, v160
	ds_bpermute_b32 v159, v207, v161
	v_pk_mul_f32 v[156:157], v[156:157], v[130:131]
	s_nop 0
	v_sub_f32_e32 v165, 1.0, v157
	v_add_f32_e32 v164, -1.0, v165
	v_log_f32_e32 v165, v165
	v_rcp_f32_e32 v164, v164
	s_nop 0
	v_mul_f32_e32 v164, v157, v164
	v_mul_f32_e32 v165, 0x3f317218, v165
	v_cmp_eq_f32_e64 s[34:35], 0, v165
	v_mul_f32_e64 v164, -v165, v164
	s_nop 0
	v_cndmask_b32_e64 v165, v164, -v157, s[34:35]
	s_nop 0
	s_nop 0
	v_mov_b32_dpp v167, v165 row_shr:1 row_mask:0xf bank_mask:0xf bound_ctrl:1
	v_sub_f32_e32 v164, 1.0, v156
	v_add_f32_e32 v140, -1.0, v164
	v_log_f32_e32 v164, v164
	v_rcp_f32_e32 v140, v140
	s_nop 0
	v_mul_f32_e32 v140, v156, v140
	v_mul_f32_e32 v164, 0x3f317218, v164
	v_cmp_eq_f32_e64 s[34:35], 0, v164
	v_mul_f32_e64 v140, -v164, v140
	s_nop 0
	v_cndmask_b32_e64 v164, v140, -v156, s[34:35]
	v_mul_f32_e32 v140, 0x3fb8aa3b, v96
	v_exp_f32_e32 v140, v140
	v_mov_b32_dpp v166, v164 row_shr:1 row_mask:0xf bank_mask:0xf bound_ctrl:1
	v_pk_add_f32 v[164:165], v[164:165], v[166:167]
	v_add_f32_e32 v140, 1.0, v140
	s_nop 0
	v_mov_b32_dpp v166, v164 row_shr:2 row_mask:0xf bank_mask:0xf bound_ctrl:1
	v_mov_b32_dpp v167, v165 row_shr:2 row_mask:0xf bank_mask:0xf bound_ctrl:1
	v_pk_add_f32 v[164:165], v[164:165], v[166:167]
	v_rcp_f32_e32 v170, v140
	s_nop 0
	v_mov_b32_dpp v166, v164 row_shr:4 row_mask:0xf bank_mask:0xf bound_ctrl:1
	v_mov_b32_dpp v167, v165 row_shr:4 row_mask:0xf bank_mask:0xf bound_ctrl:1
	v_pk_add_f32 v[164:165], v[164:165], v[166:167]
	v_mul_f32_e32 v167, 0x3fb8aa3b, v97
	v_exp_f32_e32 v168, v167
	v_mov_b32_dpp v166, v164 row_shr:8 row_mask:0xf bank_mask:0xf bound_ctrl:1
	v_mov_b32_dpp v167, v165 row_shr:8 row_mask:0xf bank_mask:0xf bound_ctrl:1
	v_add_f32_e32 v140, 1.0, v168
	v_rcp_f32_e32 v171, v140
	v_pk_add_f32 v[168:169], v[164:165], v[166:167]
	ds_bpermute_b32 v166, v207, v168
	ds_bpermute_b32 v167, v207, v169
	v_pk_mul_f32 v[164:165], v[170:171], v[128:129]
	s_nop 0
	v_sub_f32_e32 v171, 1.0, v165
	v_add_f32_e32 v170, -1.0, v171
	v_log_f32_e32 v171, v171
	v_rcp_f32_e32 v170, v170
	s_nop 0
	v_mul_f32_e32 v170, v165, v170
	v_mul_f32_e32 v171, 0x3f317218, v171
	v_cmp_eq_f32_e64 s[34:35], 0, v171
	v_mul_f32_e64 v170, -v171, v170
	s_nop 0
	v_cndmask_b32_e64 v171, v170, -v165, s[34:35]
	s_nop 0
	s_nop 0
	v_mov_b32_dpp v173, v171 row_shr:1 row_mask:0xf bank_mask:0xf bound_ctrl:1
	v_sub_f32_e32 v170, 1.0, v164
	v_add_f32_e32 v140, -1.0, v170
	v_log_f32_e32 v170, v170
	v_rcp_f32_e32 v140, v140
	s_nop 0
	v_mul_f32_e32 v140, v164, v140
	v_mul_f32_e32 v170, 0x3f317218, v170
	v_cmp_eq_f32_e64 s[34:35], 0, v170
	v_mul_f32_e64 v140, -v170, v140
	s_nop 0
	v_cndmask_b32_e64 v170, v140, -v164, s[34:35]
	v_mul_f32_e32 v140, 0x3fb8aa3b, v98
	v_exp_f32_e32 v140, v140
	v_mov_b32_dpp v172, v170 row_shr:1 row_mask:0xf bank_mask:0xf bound_ctrl:1
	v_pk_add_f32 v[170:171], v[170:171], v[172:173]
	v_add_f32_e32 v140, 1.0, v140
	s_nop 0
	v_mov_b32_dpp v172, v170 row_shr:2 row_mask:0xf bank_mask:0xf bound_ctrl:1
	v_mov_b32_dpp v173, v171 row_shr:2 row_mask:0xf bank_mask:0xf bound_ctrl:1
	v_pk_add_f32 v[170:171], v[170:171], v[172:173]
	v_rcp_f32_e32 v176, v140
	s_nop 0
	v_mov_b32_dpp v172, v170 row_shr:4 row_mask:0xf bank_mask:0xf bound_ctrl:1
	v_mov_b32_dpp v173, v171 row_shr:4 row_mask:0xf bank_mask:0xf bound_ctrl:1
	v_pk_add_f32 v[170:171], v[170:171], v[172:173]
	v_mul_f32_e32 v173, 0x3fb8aa3b, v99
	v_exp_f32_e32 v174, v173
	v_mov_b32_dpp v172, v170 row_shr:8 row_mask:0xf bank_mask:0xf bound_ctrl:1
	v_mov_b32_dpp v173, v171 row_shr:8 row_mask:0xf bank_mask:0xf bound_ctrl:1
	v_add_f32_e32 v140, 1.0, v174
	v_rcp_f32_e32 v177, v140
	v_pk_add_f32 v[174:175], v[170:171], v[172:173]
	ds_bpermute_b32 v170, v207, v174
	ds_bpermute_b32 v171, v207, v175
	v_pk_mul_f32 v[172:173], v[176:177], v[130:131]
	s_nop 0
	v_sub_f32_e32 v177, 1.0, v173
	v_add_f32_e32 v176, -1.0, v177
	v_log_f32_e32 v177, v177
	v_rcp_f32_e32 v176, v176
	s_nop 0
	v_mul_f32_e32 v176, v173, v176
	v_mul_f32_e32 v177, 0x3f317218, v177
	v_cmp_eq_f32_e64 s[34:35], 0, v177
	v_mul_f32_e64 v176, -v177, v176
	s_nop 0
	v_cndmask_b32_e64 v177, v176, -v173, s[34:35]
	s_nop 0
	s_nop 0
	v_mov_b32_dpp v179, v177 row_shr:1 row_mask:0xf bank_mask:0xf bound_ctrl:1
	v_sub_f32_e32 v176, 1.0, v172
	v_add_f32_e32 v140, -1.0, v176
	v_log_f32_e32 v176, v176
	v_rcp_f32_e32 v140, v140
	s_nop 0
	v_mul_f32_e32 v140, v172, v140
	v_mul_f32_e32 v176, 0x3f317218, v176
	v_cmp_eq_f32_e64 s[34:35], 0, v176
	v_mul_f32_e64 v140, -v176, v140
	s_nop 0
	v_cndmask_b32_e64 v176, v140, -v172, s[34:35]
	v_mul_f32_e32 v140, 0x3fb8aa3b, v80
	v_exp_f32_e32 v140, v140
	v_mov_b32_dpp v178, v176 row_shr:1 row_mask:0xf bank_mask:0xf bound_ctrl:1
	v_pk_add_f32 v[176:177], v[176:177], v[178:179]
	v_add_f32_e32 v140, 1.0, v140
	s_nop 0
	v_mov_b32_dpp v178, v176 row_shr:2 row_mask:0xf bank_mask:0xf bound_ctrl:1
	v_mov_b32_dpp v179, v177 row_shr:2 row_mask:0xf bank_mask:0xf bound_ctrl:1
	v_pk_add_f32 v[176:177], v[176:177], v[178:179]
	v_rcp_f32_e32 v182, v140
	s_nop 0
	v_mov_b32_dpp v178, v176 row_shr:4 row_mask:0xf bank_mask:0xf bound_ctrl:1
	v_mov_b32_dpp v179, v177 row_shr:4 row_mask:0xf bank_mask:0xf bound_ctrl:1
	v_pk_add_f32 v[176:177], v[176:177], v[178:179]
	v_mul_f32_e32 v179, 0x3fb8aa3b, v81
	v_exp_f32_e32 v180, v179
	v_mov_b32_dpp v178, v176 row_shr:8 row_mask:0xf bank_mask:0xf bound_ctrl:1
	v_mov_b32_dpp v179, v177 row_shr:8 row_mask:0xf bank_mask:0xf bound_ctrl:1
	v_add_f32_e32 v140, 1.0, v180
	v_rcp_f32_e32 v183, v140
	v_pk_add_f32 v[180:181], v[176:177], v[178:179]
	ds_bpermute_b32 v178, v207, v180
	ds_bpermute_b32 v179, v207, v181
	v_pk_mul_f32 v[176:177], v[182:183], v[128:129]
	s_nop 0
	v_sub_f32_e32 v183, 1.0, v177
	v_add_f32_e32 v182, -1.0, v183
	v_log_f32_e32 v183, v183
	v_rcp_f32_e32 v182, v182
	s_nop 0
	v_mul_f32_e32 v182, v177, v182
	v_mul_f32_e32 v183, 0x3f317218, v183
	v_cmp_eq_f32_e64 s[34:35], 0, v183
	v_mul_f32_e64 v182, -v183, v182
	s_nop 0
	v_cndmask_b32_e64 v183, v182, -v177, s[34:35]
	s_nop 0
	s_nop 0
	v_mov_b32_dpp v185, v183 row_shr:1 row_mask:0xf bank_mask:0xf bound_ctrl:1
	v_sub_f32_e32 v182, 1.0, v176
	v_add_f32_e32 v140, -1.0, v182
	v_log_f32_e32 v182, v182
	v_rcp_f32_e32 v140, v140
	s_nop 0
	v_mul_f32_e32 v140, v176, v140
	v_mul_f32_e32 v182, 0x3f317218, v182
	v_cmp_eq_f32_e64 s[34:35], 0, v182
	v_mul_f32_e64 v140, -v182, v140
	s_nop 0
	v_cndmask_b32_e64 v182, v140, -v176, s[34:35]
	v_mul_f32_e32 v140, 0x3fb8aa3b, v82
	v_exp_f32_e32 v140, v140
	v_mov_b32_dpp v184, v182 row_shr:1 row_mask:0xf bank_mask:0xf bound_ctrl:1
	v_pk_add_f32 v[182:183], v[182:183], v[184:185]
	v_add_f32_e32 v140, 1.0, v140
	s_nop 0
	v_mov_b32_dpp v184, v182 row_shr:2 row_mask:0xf bank_mask:0xf bound_ctrl:1
	v_mov_b32_dpp v185, v183 row_shr:2 row_mask:0xf bank_mask:0xf bound_ctrl:1
	v_pk_add_f32 v[182:183], v[182:183], v[184:185]
	v_rcp_f32_e32 v188, v140
	s_nop 0
	v_mov_b32_dpp v184, v182 row_shr:4 row_mask:0xf bank_mask:0xf bound_ctrl:1
	v_mov_b32_dpp v185, v183 row_shr:4 row_mask:0xf bank_mask:0xf bound_ctrl:1
	v_pk_add_f32 v[182:183], v[182:183], v[184:185]
	v_mul_f32_e32 v185, 0x3fb8aa3b, v83
	v_exp_f32_e32 v186, v185
	v_mov_b32_dpp v184, v182 row_shr:8 row_mask:0xf bank_mask:0xf bound_ctrl:1
	v_mov_b32_dpp v185, v183 row_shr:8 row_mask:0xf bank_mask:0xf bound_ctrl:1
	v_add_f32_e32 v140, 1.0, v186
	v_rcp_f32_e32 v189, v140
	v_pk_add_f32 v[186:187], v[182:183], v[184:185]
	ds_bpermute_b32 v182, v207, v186
	ds_bpermute_b32 v183, v207, v187
	v_pk_mul_f32 v[184:185], v[188:189], v[130:131]
	s_nop 0
	v_sub_f32_e32 v189, 1.0, v185
	v_add_f32_e32 v188, -1.0, v189
	v_log_f32_e32 v189, v189
	v_rcp_f32_e32 v188, v188
	s_nop 0
	v_mul_f32_e32 v188, v185, v188
	v_mul_f32_e32 v189, 0x3f317218, v189
	v_cmp_eq_f32_e64 s[34:35], 0, v189
	v_mul_f32_e64 v188, -v189, v188
	s_nop 0
	v_cndmask_b32_e64 v189, v188, -v185, s[34:35]
	s_nop 0
	s_nop 0
	v_mov_b32_dpp v191, v189 row_shr:1 row_mask:0xf bank_mask:0xf bound_ctrl:1
	v_sub_f32_e32 v188, 1.0, v184
	v_add_f32_e32 v140, -1.0, v188
	v_log_f32_e32 v188, v188
	v_rcp_f32_e32 v140, v140
	s_nop 0
	v_mul_f32_e32 v140, v184, v140
	v_mul_f32_e32 v188, 0x3f317218, v188
	v_cmp_eq_f32_e64 s[34:35], 0, v188
	v_mul_f32_e64 v140, -v188, v140
	s_nop 0
	v_cndmask_b32_e64 v188, v140, -v184, s[34:35]
	v_mul_f32_e32 v140, 0x3fb8aa3b, v64
	v_exp_f32_e32 v140, v140
	v_mov_b32_dpp v190, v188 row_shr:1 row_mask:0xf bank_mask:0xf bound_ctrl:1
	v_pk_add_f32 v[188:189], v[188:189], v[190:191]
	v_add_f32_e32 v140, 1.0, v140
	s_nop 0
	v_mov_b32_dpp v190, v188 row_shr:2 row_mask:0xf bank_mask:0xf bound_ctrl:1
	v_mov_b32_dpp v191, v189 row_shr:2 row_mask:0xf bank_mask:0xf bound_ctrl:1
	v_pk_add_f32 v[188:189], v[188:189], v[190:191]
	v_rcp_f32_e32 v194, v140
	s_nop 0
	v_mov_b32_dpp v190, v188 row_shr:4 row_mask:0xf bank_mask:0xf bound_ctrl:1
	v_mov_b32_dpp v191, v189 row_shr:4 row_mask:0xf bank_mask:0xf bound_ctrl:1
	v_pk_add_f32 v[188:189], v[188:189], v[190:191]
	v_mul_f32_e32 v191, 0x3fb8aa3b, v65
	v_exp_f32_e32 v192, v191
	v_mov_b32_dpp v190, v188 row_shr:8 row_mask:0xf bank_mask:0xf bound_ctrl:1
	v_mov_b32_dpp v191, v189 row_shr:8 row_mask:0xf bank_mask:0xf bound_ctrl:1
	v_add_f32_e32 v140, 1.0, v192
	v_rcp_f32_e32 v195, v140
	v_pk_add_f32 v[192:193], v[188:189], v[190:191]
	ds_bpermute_b32 v190, v207, v192
	ds_bpermute_b32 v191, v207, v193
	v_pk_mul_f32 v[188:189], v[194:195], v[128:129]
	s_nop 0
	v_sub_f32_e32 v195, 1.0, v189
	v_add_f32_e32 v194, -1.0, v195
	v_log_f32_e32 v195, v195
	v_rcp_f32_e32 v194, v194
	s_nop 0
	v_mul_f32_e32 v194, v189, v194
	v_mul_f32_e32 v195, 0x3f317218, v195
	v_cmp_eq_f32_e64 s[34:35], 0, v195
	v_mul_f32_e64 v194, -v195, v194
	s_nop 0
	v_cndmask_b32_e64 v195, v194, -v189, s[34:35]
	s_nop 0
	s_nop 0
	v_mov_b32_dpp v197, v195 row_shr:1 row_mask:0xf bank_mask:0xf bound_ctrl:1
	v_sub_f32_e32 v194, 1.0, v188
	v_add_f32_e32 v140, -1.0, v194
	v_log_f32_e32 v194, v194
	v_rcp_f32_e32 v140, v140
	s_nop 0
	v_mul_f32_e32 v140, v188, v140
	v_mul_f32_e32 v194, 0x3f317218, v194
	v_cmp_eq_f32_e64 s[34:35], 0, v194
	v_mul_f32_e64 v140, -v194, v140
	s_nop 0
	v_cndmask_b32_e64 v194, v140, -v188, s[34:35]
	v_mul_f32_e32 v140, 0x3fb8aa3b, v66
	v_exp_f32_e32 v140, v140
	v_mov_b32_dpp v196, v194 row_shr:1 row_mask:0xf bank_mask:0xf bound_ctrl:1
	v_pk_add_f32 v[194:195], v[194:195], v[196:197]
	v_add_f32_e32 v140, 1.0, v140
	s_nop 0
	v_mov_b32_dpp v196, v194 row_shr:2 row_mask:0xf bank_mask:0xf bound_ctrl:1
	v_mov_b32_dpp v197, v195 row_shr:2 row_mask:0xf bank_mask:0xf bound_ctrl:1
	v_pk_add_f32 v[194:195], v[194:195], v[196:197]
	v_rcp_f32_e32 v200, v140
	s_nop 0
	v_mov_b32_dpp v196, v194 row_shr:4 row_mask:0xf bank_mask:0xf bound_ctrl:1
	v_mov_b32_dpp v197, v195 row_shr:4 row_mask:0xf bank_mask:0xf bound_ctrl:1
	v_pk_add_f32 v[194:195], v[194:195], v[196:197]
	v_mul_f32_e32 v197, 0x3fb8aa3b, v67
	v_exp_f32_e32 v198, v197
	v_mov_b32_dpp v196, v194 row_shr:8 row_mask:0xf bank_mask:0xf bound_ctrl:1
	v_mov_b32_dpp v197, v195 row_shr:8 row_mask:0xf bank_mask:0xf bound_ctrl:1
	v_add_f32_e32 v140, 1.0, v198
	v_rcp_f32_e32 v201, v140
	v_pk_add_f32 v[198:199], v[194:195], v[196:197]
	ds_bpermute_b32 v196, v207, v198
	ds_bpermute_b32 v197, v207, v199
	v_pk_mul_f32 v[194:195], v[200:201], v[130:131]
	s_nop 0
	v_sub_f32_e32 v163, 1.0, v195
	v_add_f32_e32 v162, -1.0, v163
	v_log_f32_e32 v163, v163
	v_rcp_f32_e32 v162, v162
	s_nop 0
	v_mul_f32_e32 v162, v195, v162
	v_mul_f32_e32 v163, 0x3f317218, v163
	v_cmp_eq_f32_e64 s[34:35], 0, v163
	v_mul_f32_e64 v162, -v163, v162
	s_nop 0
	v_cndmask_b32_e64 v163, v162, -v195, s[34:35]
	s_and_b64 vcc, exec, s[8:9]
	s_nop 0
	v_mov_b32_dpp v201, v163 row_shr:1 row_mask:0xf bank_mask:0xf bound_ctrl:1
	v_sub_f32_e32 v162, 1.0, v194
	v_add_f32_e32 v140, -1.0, v162
	v_log_f32_e32 v162, v162
	v_rcp_f32_e32 v140, v140
	s_nop 0
	v_mul_f32_e32 v140, v194, v140
	v_mul_f32_e32 v162, 0x3f317218, v162
	v_cmp_eq_f32_e64 s[34:35], 0, v162
	v_mul_f32_e64 v140, -v162, v140
	s_nop 0
	v_cndmask_b32_e64 v162, v140, -v194, s[34:35]
	s_nop 1
	v_mov_b32_dpp v200, v162 row_shr:1 row_mask:0xf bank_mask:0xf bound_ctrl:1
	v_pk_add_f32 v[162:163], v[162:163], v[200:201]
	s_nop 1
	v_mov_b32_dpp v200, v162 row_shr:2 row_mask:0xf bank_mask:0xf bound_ctrl:1
	v_mov_b32_dpp v201, v163 row_shr:2 row_mask:0xf bank_mask:0xf bound_ctrl:1
	v_pk_add_f32 v[162:163], v[162:163], v[200:201]
	s_nop 1
	v_mov_b32_dpp v200, v162 row_shr:4 row_mask:0xf bank_mask:0xf bound_ctrl:1
	v_mov_b32_dpp v201, v163 row_shr:4 row_mask:0xf bank_mask:0xf bound_ctrl:1
	v_pk_add_f32 v[162:163], v[162:163], v[200:201]
	s_nop 1
	v_mov_b32_dpp v200, v162 row_shr:8 row_mask:0xf bank_mask:0xf bound_ctrl:1
	v_mov_b32_dpp v201, v163 row_shr:8 row_mask:0xf bank_mask:0xf bound_ctrl:1
	v_pk_add_f32 v[200:201], v[162:163], v[200:201]
	ds_bpermute_b32 v162, v207, v200
	ds_bpermute_b32 v163, v207, v201
	s_cbranch_vccnz .LBB0_2331
	s_waitcnt lgkmcnt(14)
	v_pk_add_f32 v[158:159], v[158:159], 0 op_sel_hi:[1,0]
	v_pk_add_f32 v[160:161], v[160:161], 0 op_sel_hi:[1,0]
	v_pk_add_f32 v[174:175], v[158:159], v[174:175]
	s_waitcnt lgkmcnt(10)
	v_pk_add_f32 v[158:159], v[158:159], v[170:171]
	v_pk_add_f32 v[168:169], v[168:169], 0 op_sel_hi:[1,0]
	s_waitcnt lgkmcnt(6)
	v_pk_add_f32 v[170:171], v[158:159], v[182:183]
	v_pk_add_f32 v[186:187], v[158:159], v[186:187]
	v_pk_add_f32 v[158:159], v[166:167], 0 op_sel_hi:[1,0]
	s_waitcnt lgkmcnt(2)
	v_pk_add_f32 v[182:183], v[170:171], v[196:197]
	v_pk_add_f32 v[180:181], v[158:159], v[180:181]
	v_pk_add_f32 v[158:159], v[158:159], v[178:179]
	v_pk_add_f32 v[198:199], v[170:171], v[198:199]
	v_pk_add_f32 v[166:167], v[158:159], v[190:191]
	v_pk_add_f32 v[192:193], v[158:159], v[192:193]
	s_waitcnt lgkmcnt(0)
	v_pk_add_f32 v[190:191], v[166:167], v[162:163]
	v_pk_add_f32 v[200:201], v[166:167], v[200:201]
	v_mov_b32_e32 v179, v191
	v_mov_b32_e32 v178, v190
	v_mov_b32_e32 v171, v183
	v_mov_b32_e32 v170, v182
	v_mov_b32_e32 v167, v191
	v_mov_b32_e32 v166, v190
	v_mov_b32_e32 v159, v183
	v_mov_b32_e32 v158, v182
	v_mov_b64_e32 v[162:163], v[190:191]
	v_mov_b64_e32 v[196:197], v[182:183]

.LBB0_2339:
	s_or_b64 exec, exec, s[68:69]
	v_mul_f32_e32 v140, 0x3fb8aa3b, v48
	v_mul_f32_e32 v154, 0x3fb8aa3b, v49
	v_exp_f32_e32 v140, v140
	v_exp_f32_e32 v154, v154
	v_add_f32_e32 v140, 1.0, v140
	v_add_f32_e32 v155, 1.0, v154
	v_rcp_f32_e32 v154, v140
	v_rcp_f32_e32 v155, v155
	s_nop 0
	v_pk_mul_f32 v[154:155], v[154:155], v[128:129]
	s_nop 0
	s_waitcnt lgkmcnt(1)
	s_waitcnt lgkmcnt(0)
	v_mov_b64_e32 v[164:165], s[38:39]
	v_sub_f32_e32 v157, 1.0, v155
	v_add_f32_e32 v156, -1.0, v157
	v_log_f32_e32 v157, v157
	v_rcp_f32_e32 v156, v156
	s_nop 0
	v_mul_f32_e32 v156, v155, v156
	v_mul_f32_e32 v157, 0x3f317218, v157
	v_cmp_eq_f32_e64 s[34:35], 0, v157
	v_mul_f32_e64 v156, -v157, v156
	s_nop 0
	v_cndmask_b32_e64 v157, v156, -v155, s[34:35]
	s_nop 0
	s_nop 0
	v_mov_b32_dpp v159, v157 row_shr:1 row_mask:0xf bank_mask:0xf bound_ctrl:1
	v_sub_f32_e32 v156, 1.0, v154
	v_add_f32_e32 v140, -1.0, v156
	v_log_f32_e32 v156, v156
	v_rcp_f32_e32 v140, v140
	s_nop 0
	v_mul_f32_e32 v140, v154, v140
	v_mul_f32_e32 v156, 0x3f317218, v156
	v_cmp_eq_f32_e64 s[34:35], 0, v156
	v_mul_f32_e64 v140, -v156, v140
	s_nop 0
	v_cndmask_b32_e64 v156, v140, -v154, s[34:35]
	v_mul_f32_e32 v140, 0x3fb8aa3b, v50
	v_exp_f32_e32 v140, v140
	v_mov_b32_dpp v158, v156 row_shr:1 row_mask:0xf bank_mask:0xf bound_ctrl:1
	v_pk_add_f32 v[156:157], v[156:157], v[158:159]
	v_add_f32_e32 v140, 1.0, v140
	s_nop 0
	v_mov_b32_dpp v158, v156 row_shr:2 row_mask:0xf bank_mask:0xf bound_ctrl:1
	v_mov_b32_dpp v159, v157 row_shr:2 row_mask:0xf bank_mask:0xf bound_ctrl:1
	v_pk_add_f32 v[156:157], v[156:157], v[158:159]
	v_rcp_f32_e32 v162, v140
	s_nop 0
	v_mov_b32_dpp v158, v156 row_shr:4 row_mask:0xf bank_mask:0xf bound_ctrl:1
	v_mov_b32_dpp v159, v157 row_shr:4 row_mask:0xf bank_mask:0xf bound_ctrl:1
	v_pk_add_f32 v[156:157], v[156:157], v[158:159]
	v_mul_f32_e32 v159, 0x3fb8aa3b, v51
	v_exp_f32_e32 v160, v159
	v_mov_b32_dpp v158, v156 row_shr:8 row_mask:0xf bank_mask:0xf bound_ctrl:1
	v_mov_b32_dpp v159, v157 row_shr:8 row_mask:0xf bank_mask:0xf bound_ctrl:1
	v_add_f32_e32 v140, 1.0, v160
	v_rcp_f32_e32 v163, v140
	v_pk_add_f32 v[160:161], v[156:157], v[158:159]
	ds_bpermute_b32 v158, v207, v160
	ds_bpermute_b32 v159, v207, v161
	v_pk_mul_f32 v[156:157], v[162:163], v[130:131]
	s_nop 0
	v_sub_f32_e32 v163, 1.0, v157
	v_add_f32_e32 v162, -1.0, v163
	v_log_f32_e32 v163, v163
	v_rcp_f32_e32 v162, v162
	s_nop 0
	v_mul_f32_e32 v162, v157, v162
	v_mul_f32_e32 v163, 0x3f317218, v163
	v_cmp_eq_f32_e64 s[34:35], 0, v163
	v_mul_f32_e64 v162, -v163, v162
	s_nop 0
	v_cndmask_b32_e64 v163, v162, -v157, s[34:35]
	s_nop 0
	s_nop 0
	v_mov_b32_dpp v167, v163 row_shr:1 row_mask:0xf bank_mask:0xf bound_ctrl:1
	v_sub_f32_e32 v162, 1.0, v156
	v_add_f32_e32 v140, -1.0, v162
	v_log_f32_e32 v162, v162
	v_rcp_f32_e32 v140, v140
	s_nop 0
	v_mul_f32_e32 v140, v156, v140
	v_mul_f32_e32 v162, 0x3f317218, v162
	v_cmp_eq_f32_e64 s[34:35], 0, v162
	v_mul_f32_e64 v140, -v162, v140
	s_nop 0
	v_cndmask_b32_e64 v162, v140, -v156, s[34:35]
	v_mul_f32_e32 v140, 0x3fb8aa3b, v32
	v_exp_f32_e32 v140, v140
	v_mov_b32_dpp v166, v162 row_shr:1 row_mask:0xf bank_mask:0xf bound_ctrl:1
	v_pk_add_f32 v[162:163], v[162:163], v[166:167]
	v_add_f32_e32 v140, 1.0, v140
	s_nop 0
	v_mov_b32_dpp v166, v162 row_shr:2 row_mask:0xf bank_mask:0xf bound_ctrl:1
	v_mov_b32_dpp v167, v163 row_shr:2 row_mask:0xf bank_mask:0xf bound_ctrl:1
	v_pk_add_f32 v[162:163], v[162:163], v[166:167]
	v_rcp_f32_e32 v170, v140
	s_nop 0
	v_mov_b32_dpp v166, v162 row_shr:4 row_mask:0xf bank_mask:0xf bound_ctrl:1
	v_mov_b32_dpp v167, v163 row_shr:4 row_mask:0xf bank_mask:0xf bound_ctrl:1
	v_pk_add_f32 v[162:163], v[162:163], v[166:167]
	v_mul_f32_e32 v167, 0x3fb8aa3b, v33
	v_exp_f32_e32 v168, v167
	v_mov_b32_dpp v166, v162 row_shr:8 row_mask:0xf bank_mask:0xf bound_ctrl:1
	v_mov_b32_dpp v167, v163 row_shr:8 row_mask:0xf bank_mask:0xf bound_ctrl:1
	v_add_f32_e32 v140, 1.0, v168
	v_rcp_f32_e32 v171, v140
	v_pk_add_f32 v[168:169], v[162:163], v[166:167]
	ds_bpermute_b32 v166, v207, v168
	ds_bpermute_b32 v167, v207, v169
	v_pk_mul_f32 v[162:163], v[170:171], v[128:129]
	s_nop 0
	v_sub_f32_e32 v171, 1.0, v163
	v_add_f32_e32 v170, -1.0, v171
	v_log_f32_e32 v171, v171
	v_rcp_f32_e32 v170, v170
	s_nop 0
	v_mul_f32_e32 v170, v163, v170
	v_mul_f32_e32 v171, 0x3f317218, v171
	v_cmp_eq_f32_e64 s[34:35], 0, v171
	v_mul_f32_e64 v170, -v171, v170
	s_nop 0
	v_cndmask_b32_e64 v171, v170, -v163, s[34:35]
	s_nop 0
	s_nop 0
	v_mov_b32_dpp v173, v171 row_shr:1 row_mask:0xf bank_mask:0xf bound_ctrl:1
	v_sub_f32_e32 v170, 1.0, v162
	v_add_f32_e32 v140, -1.0, v170
	v_log_f32_e32 v170, v170
	v_rcp_f32_e32 v140, v140
	s_nop 0
	v_mul_f32_e32 v140, v162, v140
	v_mul_f32_e32 v170, 0x3f317218, v170
	v_cmp_eq_f32_e64 s[34:35], 0, v170
	v_mul_f32_e64 v140, -v170, v140
	s_nop 0
	v_cndmask_b32_e64 v170, v140, -v162, s[34:35]
	v_mul_f32_e32 v140, 0x3fb8aa3b, v34
	v_exp_f32_e32 v140, v140
	v_mov_b32_dpp v172, v170 row_shr:1 row_mask:0xf bank_mask:0xf bound_ctrl:1
	v_pk_add_f32 v[170:171], v[170:171], v[172:173]
	v_add_f32_e32 v140, 1.0, v140
	s_nop 0
	v_mov_b32_dpp v172, v170 row_shr:2 row_mask:0xf bank_mask:0xf bound_ctrl:1
	v_mov_b32_dpp v173, v171 row_shr:2 row_mask:0xf bank_mask:0xf bound_ctrl:1
	v_pk_add_f32 v[170:171], v[170:171], v[172:173]
	v_rcp_f32_e32 v176, v140
	s_nop 0
	v_mov_b32_dpp v172, v170 row_shr:4 row_mask:0xf bank_mask:0xf bound_ctrl:1
	v_mov_b32_dpp v173, v171 row_shr:4 row_mask:0xf bank_mask:0xf bound_ctrl:1
	v_pk_add_f32 v[170:171], v[170:171], v[172:173]
	v_mul_f32_e32 v173, 0x3fb8aa3b, v35
	v_exp_f32_e32 v174, v173
	v_mov_b32_dpp v172, v170 row_shr:8 row_mask:0xf bank_mask:0xf bound_ctrl:1
	v_mov_b32_dpp v173, v171 row_shr:8 row_mask:0xf bank_mask:0xf bound_ctrl:1
	v_add_f32_e32 v140, 1.0, v174
	v_rcp_f32_e32 v177, v140
	v_pk_add_f32 v[174:175], v[170:171], v[172:173]
	ds_bpermute_b32 v170, v207, v174
	ds_bpermute_b32 v171, v207, v175
	v_pk_mul_f32 v[172:173], v[176:177], v[130:131]
	s_nop 0
	v_sub_f32_e32 v177, 1.0, v173
	v_add_f32_e32 v176, -1.0, v177
	v_log_f32_e32 v177, v177
	v_rcp_f32_e32 v176, v176
	s_nop 0
	v_mul_f32_e32 v176, v173, v176
	v_mul_f32_e32 v177, 0x3f317218, v177
	v_cmp_eq_f32_e64 s[34:35], 0, v177
	v_mul_f32_e64 v176, -v177, v176
	s_nop 0
	v_cndmask_b32_e64 v177, v176, -v173, s[34:35]
	s_nop 0
	s_nop 0
	v_mov_b32_dpp v179, v177 row_shr:1 row_mask:0xf bank_mask:0xf bound_ctrl:1
	v_sub_f32_e32 v176, 1.0, v172
	v_add_f32_e32 v140, -1.0, v176
	v_log_f32_e32 v176, v176
	v_rcp_f32_e32 v140, v140
	s_nop 0
	v_mul_f32_e32 v140, v172, v140
	v_mul_f32_e32 v176, 0x3f317218, v176
	v_cmp_eq_f32_e64 s[34:35], 0, v176
	v_mul_f32_e64 v140, -v176, v140
	s_nop 0
	v_cndmask_b32_e64 v176, v140, -v172, s[34:35]
	v_mul_f32_e32 v140, 0x3fb8aa3b, v16
	v_exp_f32_e32 v140, v140
	v_mov_b32_dpp v178, v176 row_shr:1 row_mask:0xf bank_mask:0xf bound_ctrl:1
	v_pk_add_f32 v[176:177], v[176:177], v[178:179]
	v_add_f32_e32 v140, 1.0, v140
	s_nop 0
	v_mov_b32_dpp v178, v176 row_shr:2 row_mask:0xf bank_mask:0xf bound_ctrl:1
	v_mov_b32_dpp v179, v177 row_shr:2 row_mask:0xf bank_mask:0xf bound_ctrl:1
	v_pk_add_f32 v[176:177], v[176:177], v[178:179]
	v_rcp_f32_e32 v182, v140
	s_nop 0
	v_mov_b32_dpp v178, v176 row_shr:4 row_mask:0xf bank_mask:0xf bound_ctrl:1
	v_mov_b32_dpp v179, v177 row_shr:4 row_mask:0xf bank_mask:0xf bound_ctrl:1
	v_pk_add_f32 v[176:177], v[176:177], v[178:179]
	v_mul_f32_e32 v179, 0x3fb8aa3b, v17
	v_exp_f32_e32 v180, v179
	v_mov_b32_dpp v178, v176 row_shr:8 row_mask:0xf bank_mask:0xf bound_ctrl:1
	v_mov_b32_dpp v179, v177 row_shr:8 row_mask:0xf bank_mask:0xf bound_ctrl:1
	v_add_f32_e32 v140, 1.0, v180
	v_rcp_f32_e32 v183, v140
	v_pk_add_f32 v[180:181], v[176:177], v[178:179]
	ds_bpermute_b32 v178, v207, v180
	ds_bpermute_b32 v179, v207, v181
	v_pk_mul_f32 v[176:177], v[182:183], v[128:129]
	s_nop 0
	v_sub_f32_e32 v183, 1.0, v177
	v_add_f32_e32 v182, -1.0, v183
	v_log_f32_e32 v183, v183
	v_rcp_f32_e32 v182, v182
	s_nop 0
	v_mul_f32_e32 v182, v177, v182
	v_mul_f32_e32 v183, 0x3f317218, v183
	v_cmp_eq_f32_e64 s[34:35], 0, v183
	v_mul_f32_e64 v182, -v183, v182
	s_nop 0
	v_cndmask_b32_e64 v183, v182, -v177, s[34:35]
	s_nop 0
	s_nop 0
	v_mov_b32_dpp v185, v183 row_shr:1 row_mask:0xf bank_mask:0xf bound_ctrl:1
	v_sub_f32_e32 v182, 1.0, v176
	v_add_f32_e32 v140, -1.0, v182
	v_log_f32_e32 v182, v182
	v_rcp_f32_e32 v140, v140
	s_nop 0
	v_mul_f32_e32 v140, v176, v140
	v_mul_f32_e32 v182, 0x3f317218, v182
	v_cmp_eq_f32_e64 s[34:35], 0, v182
	v_mul_f32_e64 v140, -v182, v140
	s_nop 0
	v_cndmask_b32_e64 v182, v140, -v176, s[34:35]
	v_mul_f32_e32 v140, 0x3fb8aa3b, v18
	v_exp_f32_e32 v140, v140
	v_mov_b32_dpp v184, v182 row_shr:1 row_mask:0xf bank_mask:0xf bound_ctrl:1
	v_pk_add_f32 v[182:183], v[182:183], v[184:185]
	v_add_f32_e32 v140, 1.0, v140
	s_nop 0
	v_mov_b32_dpp v184, v182 row_shr:2 row_mask:0xf bank_mask:0xf bound_ctrl:1
	v_mov_b32_dpp v185, v183 row_shr:2 row_mask:0xf bank_mask:0xf bound_ctrl:1
	v_pk_add_f32 v[182:183], v[182:183], v[184:185]
	v_rcp_f32_e32 v188, v140
	s_nop 0
	v_mov_b32_dpp v184, v182 row_shr:4 row_mask:0xf bank_mask:0xf bound_ctrl:1
	v_mov_b32_dpp v185, v183 row_shr:4 row_mask:0xf bank_mask:0xf bound_ctrl:1
	v_pk_add_f32 v[182:183], v[182:183], v[184:185]
	v_mul_f32_e32 v185, 0x3fb8aa3b, v19
	v_exp_f32_e32 v186, v185
	v_mov_b32_dpp v184, v182 row_shr:8 row_mask:0xf bank_mask:0xf bound_ctrl:1
	v_mov_b32_dpp v185, v183 row_shr:8 row_mask:0xf bank_mask:0xf bound_ctrl:1
	v_add_f32_e32 v140, 1.0, v186
	v_rcp_f32_e32 v189, v140
	v_pk_add_f32 v[186:187], v[182:183], v[184:185]
	ds_bpermute_b32 v182, v207, v186
	ds_bpermute_b32 v183, v207, v187
	v_pk_mul_f32 v[184:185], v[188:189], v[130:131]
	s_nop 0
	v_sub_f32_e32 v189, 1.0, v185
	v_add_f32_e32 v188, -1.0, v189
	v_log_f32_e32 v189, v189
	v_rcp_f32_e32 v188, v188
	s_nop 0
	v_mul_f32_e32 v188, v185, v188
	v_mul_f32_e32 v189, 0x3f317218, v189
	v_cmp_eq_f32_e64 s[34:35], 0, v189
	v_mul_f32_e64 v188, -v189, v188
	s_nop 0
	v_cndmask_b32_e64 v189, v188, -v185, s[34:35]
	s_nop 0
	s_nop 0
	v_mov_b32_dpp v191, v189 row_shr:1 row_mask:0xf bank_mask:0xf bound_ctrl:1
	v_sub_f32_e32 v188, 1.0, v184
	v_add_f32_e32 v140, -1.0, v188
	v_log_f32_e32 v188, v188
	v_rcp_f32_e32 v140, v140
	s_nop 0
	v_mul_f32_e32 v140, v184, v140
	v_mul_f32_e32 v188, 0x3f317218, v188
	v_cmp_eq_f32_e64 s[34:35], 0, v188
	v_mul_f32_e64 v140, -v188, v140
	s_nop 0
	v_cndmask_b32_e64 v188, v140, -v184, s[34:35]
	v_mul_f32_e32 v140, 0x3fb8aa3b, v0
	v_exp_f32_e32 v140, v140
	v_mov_b32_dpp v190, v188 row_shr:1 row_mask:0xf bank_mask:0xf bound_ctrl:1
	v_pk_add_f32 v[188:189], v[188:189], v[190:191]
	v_add_f32_e32 v140, 1.0, v140
	s_nop 0
	v_mov_b32_dpp v190, v188 row_shr:2 row_mask:0xf bank_mask:0xf bound_ctrl:1
	v_mov_b32_dpp v191, v189 row_shr:2 row_mask:0xf bank_mask:0xf bound_ctrl:1
	v_pk_add_f32 v[188:189], v[188:189], v[190:191]
	v_rcp_f32_e32 v192, v140
	s_nop 0
	v_mov_b32_dpp v190, v188 row_shr:4 row_mask:0xf bank_mask:0xf bound_ctrl:1
	v_mov_b32_dpp v191, v189 row_shr:4 row_mask:0xf bank_mask:0xf bound_ctrl:1
	v_pk_add_f32 v[188:189], v[188:189], v[190:191]
	v_mul_f32_e32 v191, 0x3fb8aa3b, v1
	v_exp_f32_e32 v193, v191
	v_mov_b32_dpp v190, v188 row_shr:8 row_mask:0xf bank_mask:0xf bound_ctrl:1
	v_mov_b32_dpp v191, v189 row_shr:8 row_mask:0xf bank_mask:0xf bound_ctrl:1
	v_pk_add_f32 v[190:191], v[188:189], v[190:191]
	v_add_f32_e32 v140, 1.0, v193
	v_rcp_f32_e32 v193, v140
	ds_bpermute_b32 v188, v207, v190
	ds_bpermute_b32 v189, v207, v191
	v_pk_mul_f32 v[128:129], v[192:193], v[128:129]
	s_nop 0
	v_sub_f32_e32 v193, 1.0, v129
	v_add_f32_e32 v192, -1.0, v193
	v_log_f32_e32 v193, v193
	v_rcp_f32_e32 v192, v192
	s_nop 0
	v_mul_f32_e32 v192, v129, v192
	v_mul_f32_e32 v193, 0x3f317218, v193
	v_cmp_eq_f32_e64 s[34:35], 0, v193
	v_mul_f32_e64 v192, -v193, v192
	s_nop 0
	v_cndmask_b32_e64 v193, v192, -v129, s[34:35]
	s_nop 0
	s_nop 0
	v_mov_b32_dpp v195, v193 row_shr:1 row_mask:0xf bank_mask:0xf bound_ctrl:1
	v_sub_f32_e32 v192, 1.0, v128
	v_add_f32_e32 v140, -1.0, v192
	v_log_f32_e32 v192, v192
	v_rcp_f32_e32 v140, v140
	s_nop 0
	v_mul_f32_e32 v140, v128, v140
	v_mul_f32_e32 v192, 0x3f317218, v192
	v_cmp_eq_f32_e64 s[34:35], 0, v192
	v_mul_f32_e64 v140, -v192, v140
	s_nop 0
	v_cndmask_b32_e64 v192, v140, -v128, s[34:35]
	v_mul_f32_e32 v140, 0x3fb8aa3b, v2
	v_exp_f32_e32 v140, v140
	v_mov_b32_dpp v194, v192 row_shr:1 row_mask:0xf bank_mask:0xf bound_ctrl:1
	v_pk_add_f32 v[192:193], v[192:193], v[194:195]
	v_add_f32_e32 v140, 1.0, v140
	s_nop 0
	v_mov_b32_dpp v194, v192 row_shr:2 row_mask:0xf bank_mask:0xf bound_ctrl:1
	v_mov_b32_dpp v195, v193 row_shr:2 row_mask:0xf bank_mask:0xf bound_ctrl:1
	v_pk_add_f32 v[192:193], v[192:193], v[194:195]
	v_rcp_f32_e32 v196, v140
	s_nop 0
	v_mov_b32_dpp v194, v192 row_shr:4 row_mask:0xf bank_mask:0xf bound_ctrl:1
	v_mov_b32_dpp v195, v193 row_shr:4 row_mask:0xf bank_mask:0xf bound_ctrl:1
	v_pk_add_f32 v[192:193], v[192:193], v[194:195]
	v_mul_f32_e32 v195, 0x3fb8aa3b, v3
	v_exp_f32_e32 v197, v195
	v_mov_b32_dpp v194, v192 row_shr:8 row_mask:0xf bank_mask:0xf bound_ctrl:1
	v_mov_b32_dpp v195, v193 row_shr:8 row_mask:0xf bank_mask:0xf bound_ctrl:1
	v_pk_add_f32 v[194:195], v[192:193], v[194:195]
	v_add_f32_e32 v140, 1.0, v197
	v_rcp_f32_e32 v197, v140
	ds_bpermute_b32 v192, v207, v194
	ds_bpermute_b32 v193, v207, v195
	v_pk_mul_f32 v[130:131], v[196:197], v[130:131]
	s_nop 0
	v_sub_f32_e32 v165, 1.0, v131
	v_add_f32_e32 v164, -1.0, v165
	v_log_f32_e32 v165, v165
	v_rcp_f32_e32 v164, v164
	s_nop 0
	v_mul_f32_e32 v164, v131, v164
	v_mul_f32_e32 v165, 0x3f317218, v165
	v_cmp_eq_f32_e64 s[34:35], 0, v165
	v_mul_f32_e64 v164, -v165, v164
	s_nop 0
	v_cndmask_b32_e64 v165, v164, -v131, s[34:35]
	s_and_b64 vcc, exec, s[8:9]
	s_nop 0
	v_mov_b32_dpp v197, v165 row_shr:1 row_mask:0xf bank_mask:0xf bound_ctrl:1
	v_sub_f32_e32 v164, 1.0, v130
	v_add_f32_e32 v140, -1.0, v164
	v_log_f32_e32 v164, v164
	v_rcp_f32_e32 v140, v140
	s_nop 0
	v_mul_f32_e32 v140, v130, v140
	v_mul_f32_e32 v164, 0x3f317218, v164
	v_cmp_eq_f32_e64 s[34:35], 0, v164
	v_mul_f32_e64 v140, -v164, v140
	s_nop 0
	v_cndmask_b32_e64 v164, v140, -v130, s[34:35]
	s_nop 1
	v_mov_b32_dpp v196, v164 row_shr:1 row_mask:0xf bank_mask:0xf bound_ctrl:1
	v_pk_add_f32 v[164:165], v[164:165], v[196:197]
	s_nop 1
	v_mov_b32_dpp v196, v164 row_shr:2 row_mask:0xf bank_mask:0xf bound_ctrl:1
	v_mov_b32_dpp v197, v165 row_shr:2 row_mask:0xf bank_mask:0xf bound_ctrl:1
	v_pk_add_f32 v[164:165], v[164:165], v[196:197]
	s_nop 1
	v_mov_b32_dpp v196, v164 row_shr:4 row_mask:0xf bank_mask:0xf bound_ctrl:1
	v_mov_b32_dpp v197, v165 row_shr:4 row_mask:0xf bank_mask:0xf bound_ctrl:1
	v_pk_add_f32 v[164:165], v[164:165], v[196:197]
	s_nop 1
	v_mov_b32_dpp v196, v164 row_shr:8 row_mask:0xf bank_mask:0xf bound_ctrl:1
	v_mov_b32_dpp v197, v165 row_shr:8 row_mask:0xf bank_mask:0xf bound_ctrl:1
	v_pk_add_f32 v[196:197], v[164:165], v[196:197]
	ds_bpermute_b32 v164, v207, v196
	ds_bpermute_b32 v165, v207, v197
	s_cbranch_vccnz .LBB0_2341
	s_waitcnt lgkmcnt(14)
	v_pk_add_f32 v[158:159], v[158:159], 0 op_sel_hi:[1,0]
	v_pk_add_f32 v[160:161], v[160:161], 0 op_sel_hi:[1,0]
	v_pk_add_f32 v[174:175], v[158:159], v[174:175]
	s_waitcnt lgkmcnt(10)
	v_pk_add_f32 v[158:159], v[158:159], v[170:171]
	v_pk_add_f32 v[168:169], v[168:169], 0 op_sel_hi:[1,0]
	s_waitcnt lgkmcnt(6)
	v_pk_add_f32 v[170:171], v[158:159], v[182:183]
	v_pk_add_f32 v[186:187], v[158:159], v[186:187]
	v_pk_add_f32 v[158:159], v[166:167], 0 op_sel_hi:[1,0]
	s_waitcnt lgkmcnt(2)
	v_pk_add_f32 v[182:183], v[170:171], v[192:193]
	v_pk_add_f32 v[180:181], v[158:159], v[180:181]
	v_pk_add_f32 v[158:159], v[158:159], v[178:179]
	v_pk_add_f32 v[194:195], v[170:171], v[194:195]
	v_pk_add_f32 v[166:167], v[158:159], v[188:189]
	v_pk_add_f32 v[190:191], v[158:159], v[190:191]
	s_waitcnt lgkmcnt(0)
	v_pk_add_f32 v[188:189], v[166:167], v[164:165]
	v_pk_add_f32 v[196:197], v[166:167], v[196:197]
	v_mov_b32_e32 v179, v189
	v_mov_b32_e32 v178, v188
	v_mov_b32_e32 v171, v183
	v_mov_b32_e32 v170, v182
	v_mov_b32_e32 v167, v189
	v_mov_b32_e32 v166, v188
	v_mov_b32_e32 v159, v183
	v_mov_b32_e32 v158, v182
	v_mov_b64_e32 v[164:165], v[188:189]
	v_mov_b64_e32 v[192:193], v[182:183]
